# fused up-GEMM epilogue: packed f32 ops (v_pk_mul_f32 / v_pk_fma_f32) for the row scale, the first conv FMA and the two SiLU multiplies (192 fewer VALU instructions per unit)
# speedup vs baseline: 1.0022x; 1.0022x over previous
.LBB0_1070:
	v_add_u32_e32 v193, s54, v188
	ds_read2_b32 v[184:185], v193 offset1:16
	ds_read2_b32 v[182:183], v193 offset0:32 offset1:48
	ds_read2_b32 v[178:179], v193 offset0:64 offset1:80
	ds_read2_b32 v[176:177], v193 offset0:96 offset1:112
	s_waitcnt lgkmcnt(0)
	v_readlane_b32 s12, v254, 11
	v_readlane_b32 s13, v254, 12
	v_and_b32_e32 v180, 15, v219
	v_bfe_u32 v181, v219, 4, 2
	v_bfe_u32 v234, v219, 6, 2
	v_bfe_u32 v235, v219, 8, 1
	v_lshlrev_b32_e32 v236, 5, v234
	v_lshl_or_b32 v236, v181, 3, v236
	s_load_dwordx2 s[34:35], s[12:13], 0x88
	s_load_dwordx2 s[36:37], s[12:13], 0x90
	s_lshl_b32 s23, s67, 7
	v_or_b32_e32 v237, s23, v236
	v_lshlrev_b32_e32 v237, 2, v237
	v_lshlrev_b32_e32 v234, 10, v180
	v_lshl_add_u32 v234, v236, 2, v234
	v_lshl_add_u32 v234, v235, 11, v234
	v_add_u32_e32 v234, 0x1c800, v234
	v_lshl_or_b32 v245, v235, 6, v180
	s_lshl_b32 s23, s66, 8
	v_or_b32_e32 v245, s23, v245
	v_mul_u32_u24_e32 v245, 0x2c00, v245
	v_lshrrev_b32_e32 v221, 1, v237
	v_add_u32_e32 v245, v245, v221
	v_mul_u32_u24_e32 v181, 12, v235
	v_sub_u32_e32 v181, v180, v181
	v_add_u32_e32 v181, 2, v181
	s_lshl_b32 s23, s66, 2
	v_add_u32_e32 v181, s23, v181
	v_mul_u32_u24_e32 v181, 0x2c00, v181
	s_lshl_b32 s25, s67, 8
	v_add3_u32 v181, v181, s25, v236
	v_lshlrev_b32_e32 v181, 2, v181
	s_waitcnt lgkmcnt(0)
	s_mul_i32 s23, s68, 0x21000
	s_add_u32 s34, s34, s23
	s_addc_u32 s35, s35, 0
	s_mul_i32 s23, s68, 0xb000
	s_add_u32 s36, s36, s23
	s_addc_u32 s37, s37, 0
	v_add_u32_e32 v221, 0x16000, v237
	global_load_dwordx4 v[132:135], v221, s[34:35]
	global_load_dwordx4 v[136:139], v221, s[34:35] offset:16
	v_add_u32_e32 v240, 0xb000, v237
	global_load_dwordx4 v[140:143], v240, s[34:35]
	global_load_dwordx4 v[144:147], v240, s[34:35] offset:16
	global_load_dwordx4 v[148:151], v237, s[34:35]
	global_load_dwordx4 v[152:155], v237, s[34:35] offset:16
	global_load_dwordx4 v[156:159], v237, s[36:37]
	global_load_dwordx4 v[160:163], v237, s[36:37] offset:16
	v_add_u32_e32 v221, 0x1b800, v237
	global_load_dwordx4 v[194:197], v221, s[34:35]
	global_load_dwordx4 v[198:201], v221, s[34:35] offset:16
	v_add_u32_e32 v240, 0x10800, v237
	global_load_dwordx4 v[202:205], v240, s[34:35]
	global_load_dwordx4 v[206:209], v240, s[34:35] offset:16
	v_add_u32_e32 v221, 0x5800, v237
	global_load_dwordx4 v[210:213], v221, s[34:35]
	global_load_dwordx4 v[214:217], v221, s[34:35] offset:16
	v_add_u32_e32 v240, 0x5800, v237
	global_load_dwordx4 v[226:229], v240, s[36:37]
	global_load_dwordx4 v[230:233], v240, s[36:37] offset:16
	s_add_u32 s12, s18, 0x16000000
	s_addc_u32 s13, s19, 0
	v_pk_mul_f32 v[8:9], v[8:9], v[184:185] op_sel_hi:[1,0]
	v_pk_mul_f32 v[10:11], v[10:11], v[184:185] op_sel_hi:[1,0]
	v_pk_mul_f32 v[128:129], v[128:129], v[184:185] op_sel_hi:[1,0]
	v_pk_mul_f32 v[130:131], v[130:131], v[184:185] op_sel_hi:[1,0]
	v_pk_mul_f32 v[100:101], v[100:101], v[184:185] op_sel_hi:[1,0]
	v_pk_mul_f32 v[102:103], v[102:103], v[184:185] op_sel_hi:[1,0]
	v_pk_mul_f32 v[96:97], v[96:97], v[184:185] op_sel_hi:[1,0]
	v_pk_mul_f32 v[98:99], v[98:99], v[184:185] op_sel_hi:[1,0]
	v_pk_mul_f32 v[124:125], v[124:125], v[184:185] op_sel:[0,1] op_sel_hi:[1,1]
	v_pk_mul_f32 v[126:127], v[126:127], v[184:185] op_sel:[0,1] op_sel_hi:[1,1]
	v_pk_mul_f32 v[120:121], v[120:121], v[184:185] op_sel:[0,1] op_sel_hi:[1,1]
	v_pk_mul_f32 v[122:123], v[122:123], v[184:185] op_sel:[0,1] op_sel_hi:[1,1]
	v_pk_mul_f32 v[92:93], v[92:93], v[184:185] op_sel:[0,1] op_sel_hi:[1,1]
	v_pk_mul_f32 v[94:95], v[94:95], v[184:185] op_sel:[0,1] op_sel_hi:[1,1]
	v_pk_mul_f32 v[88:89], v[88:89], v[184:185] op_sel:[0,1] op_sel_hi:[1,1]
	v_pk_mul_f32 v[90:91], v[90:91], v[184:185] op_sel:[0,1] op_sel_hi:[1,1]
	v_pk_mul_f32 v[116:117], v[116:117], v[182:183] op_sel_hi:[1,0]
	v_pk_mul_f32 v[118:119], v[118:119], v[182:183] op_sel_hi:[1,0]
	v_pk_mul_f32 v[112:113], v[112:113], v[182:183] op_sel_hi:[1,0]
	v_pk_mul_f32 v[114:115], v[114:115], v[182:183] op_sel_hi:[1,0]
	v_pk_mul_f32 v[84:85], v[84:85], v[182:183] op_sel_hi:[1,0]
	v_pk_mul_f32 v[86:87], v[86:87], v[182:183] op_sel_hi:[1,0]
	v_pk_mul_f32 v[80:81], v[80:81], v[182:183] op_sel_hi:[1,0]
	v_pk_mul_f32 v[82:83], v[82:83], v[182:183] op_sel_hi:[1,0]
	v_pk_mul_f32 v[108:109], v[108:109], v[182:183] op_sel:[0,1] op_sel_hi:[1,1]
	v_pk_mul_f32 v[110:111], v[110:111], v[182:183] op_sel:[0,1] op_sel_hi:[1,1]
	v_pk_mul_f32 v[104:105], v[104:105], v[182:183] op_sel:[0,1] op_sel_hi:[1,1]
	v_pk_mul_f32 v[106:107], v[106:107], v[182:183] op_sel:[0,1] op_sel_hi:[1,1]
	v_pk_mul_f32 v[76:77], v[76:77], v[182:183] op_sel:[0,1] op_sel_hi:[1,1]
	v_pk_mul_f32 v[78:79], v[78:79], v[182:183] op_sel:[0,1] op_sel_hi:[1,1]
	v_pk_mul_f32 v[72:73], v[72:73], v[182:183] op_sel:[0,1] op_sel_hi:[1,1]
	v_pk_mul_f32 v[74:75], v[74:75], v[182:183] op_sel:[0,1] op_sel_hi:[1,1]
	v_pk_mul_f32 v[68:69], v[68:69], v[178:179] op_sel_hi:[1,0]
	v_pk_mul_f32 v[70:71], v[70:71], v[178:179] op_sel_hi:[1,0]
	v_pk_mul_f32 v[64:65], v[64:65], v[178:179] op_sel_hi:[1,0]
	v_pk_mul_f32 v[66:67], v[66:67], v[178:179] op_sel_hi:[1,0]
	v_pk_mul_f32 v[36:37], v[36:37], v[178:179] op_sel_hi:[1,0]
	v_pk_mul_f32 v[38:39], v[38:39], v[178:179] op_sel_hi:[1,0]
	v_pk_mul_f32 v[32:33], v[32:33], v[178:179] op_sel_hi:[1,0]
	v_pk_mul_f32 v[34:35], v[34:35], v[178:179] op_sel_hi:[1,0]
	v_pk_mul_f32 v[60:61], v[60:61], v[178:179] op_sel:[0,1] op_sel_hi:[1,1]
	v_pk_mul_f32 v[62:63], v[62:63], v[178:179] op_sel:[0,1] op_sel_hi:[1,1]
	v_pk_mul_f32 v[56:57], v[56:57], v[178:179] op_sel:[0,1] op_sel_hi:[1,1]
	v_pk_mul_f32 v[58:59], v[58:59], v[178:179] op_sel:[0,1] op_sel_hi:[1,1]
	v_pk_mul_f32 v[28:29], v[28:29], v[178:179] op_sel:[0,1] op_sel_hi:[1,1]
	v_pk_mul_f32 v[30:31], v[30:31], v[178:179] op_sel:[0,1] op_sel_hi:[1,1]
	v_pk_mul_f32 v[24:25], v[24:25], v[178:179] op_sel:[0,1] op_sel_hi:[1,1]
	v_pk_mul_f32 v[26:27], v[26:27], v[178:179] op_sel:[0,1] op_sel_hi:[1,1]
	v_pk_mul_f32 v[52:53], v[52:53], v[176:177] op_sel_hi:[1,0]
	v_pk_mul_f32 v[54:55], v[54:55], v[176:177] op_sel_hi:[1,0]
	v_pk_mul_f32 v[48:49], v[48:49], v[176:177] op_sel_hi:[1,0]
	v_pk_mul_f32 v[50:51], v[50:51], v[176:177] op_sel_hi:[1,0]
	v_pk_mul_f32 v[20:21], v[20:21], v[176:177] op_sel_hi:[1,0]
	v_pk_mul_f32 v[22:23], v[22:23], v[176:177] op_sel_hi:[1,0]
	v_pk_mul_f32 v[16:17], v[16:17], v[176:177] op_sel_hi:[1,0]
	v_pk_mul_f32 v[18:19], v[18:19], v[176:177] op_sel_hi:[1,0]
	v_pk_mul_f32 v[44:45], v[44:45], v[176:177] op_sel:[0,1] op_sel_hi:[1,1]
	v_pk_mul_f32 v[46:47], v[46:47], v[176:177] op_sel:[0,1] op_sel_hi:[1,1]
	v_pk_mul_f32 v[40:41], v[40:41], v[176:177] op_sel:[0,1] op_sel_hi:[1,1]
	v_pk_mul_f32 v[42:43], v[42:43], v[176:177] op_sel:[0,1] op_sel_hi:[1,1]
	v_pk_mul_f32 v[12:13], v[12:13], v[176:177] op_sel:[0,1] op_sel_hi:[1,1]
	v_pk_mul_f32 v[14:15], v[14:15], v[176:177] op_sel:[0,1] op_sel_hi:[1,1]
	v_pk_mul_f32 v[4:5], v[4:5], v[176:177] op_sel:[0,1] op_sel_hi:[1,1]
	v_pk_mul_f32 v[6:7], v[6:7], v[176:177] op_sel:[0,1] op_sel_hi:[1,1]
	s_mov_b32 exec_lo, 0xc000c000
	s_mov_b32 exec_hi, 0xc000c000
	ds_write_b128 v234, v[108:111] offset:2048
	ds_write_b128 v234, v[104:107] offset:2064
	ds_write_b128 v234, v[76:79] offset:2560
	ds_write_b128 v234, v[72:75] offset:2576
	s_and_b64 vcc, exec, s[16:17]
	s_cbranch_vccnz .Lfe_wr1
	ds_write_b128 v234, v[44:47] offset:6144
	ds_write_b128 v234, v[40:43] offset:6160
	ds_write_b128 v234, v[12:15] offset:6656
	ds_write_b128 v234, v[4:7] offset:6672
	v_mov_b32_e32 v246, 0
	v_mov_b32_e32 v247, 0
	v_mov_b32_e32 v248, 0
	v_mov_b32_e32 v249, 0
	s_nop 1
	ds_write_b128 v234, v[246:249] offset:0
	ds_write_b128 v234, v[246:249] offset:16
	ds_write_b128 v234, v[246:249] offset:512
	ds_write_b128 v234, v[246:249] offset:528
	s_mov_b32 exec_lo, 0x30003
	s_mov_b32 exec_hi, 0x30003
	global_store_dwordx4 v181, v[8:11], s[18:19]
	global_store_dwordx4 v181, v[128:131], s[18:19] offset:16
	global_store_dwordx4 v181, v[100:103], s[18:19] offset:512
	global_store_dwordx4 v181, v[96:99], s[18:19] offset:528
	s_branch .Lfe_join

.Lfe_join:
	s_mov_b64 exec, -1
	s_waitcnt lgkmcnt(0)
	s_barrier
	s_mov_b32 exec_lo, 0xc000c000
	s_mov_b32 exec_hi, 0xc000c000
	ds_read_b128 v[246:249], v234 offset:0
	ds_read_b128 v[250:253], v234 offset:16
	s_mov_b64 exec, -1
	s_waitcnt vmcnt(12)
	v_pk_fma_f32 v[176:177], v[132:133], v[108:109], v[156:157]
	v_pk_fma_f32 v[178:179], v[134:135], v[110:111], v[158:159]
	v_pk_fma_f32 v[182:183], v[136:137], v[104:105], v[160:161]
	v_pk_fma_f32 v[184:185], v[138:139], v[106:107], v[162:163]
	v_fmac_f32_dpp v176, v108, v140 row_shr:1 row_mask:0xf bank_mask:0xf
	v_fmac_f32_dpp v177, v109, v141 row_shr:1 row_mask:0xf bank_mask:0xf
	v_fmac_f32_dpp v178, v110, v142 row_shr:1 row_mask:0xf bank_mask:0xf
	v_fmac_f32_dpp v179, v111, v143 row_shr:1 row_mask:0xf bank_mask:0xf
	v_fmac_f32_dpp v182, v104, v144 row_shr:1 row_mask:0xf bank_mask:0xf
	v_fmac_f32_dpp v183, v105, v145 row_shr:1 row_mask:0xf bank_mask:0xf
	v_fmac_f32_dpp v184, v106, v146 row_shr:1 row_mask:0xf bank_mask:0xf
	v_fmac_f32_dpp v185, v107, v147 row_shr:1 row_mask:0xf bank_mask:0xf
	v_fmac_f32_dpp v176, v108, v148 row_shr:2 row_mask:0xf bank_mask:0xf
	v_fmac_f32_dpp v177, v109, v149 row_shr:2 row_mask:0xf bank_mask:0xf
	v_fmac_f32_dpp v178, v110, v150 row_shr:2 row_mask:0xf bank_mask:0xf
	v_fmac_f32_dpp v179, v111, v151 row_shr:2 row_mask:0xf bank_mask:0xf
	v_fmac_f32_dpp v182, v104, v152 row_shr:2 row_mask:0xf bank_mask:0xf
	v_fmac_f32_dpp v183, v105, v153 row_shr:2 row_mask:0xf bank_mask:0xf
	v_fmac_f32_dpp v184, v106, v154 row_shr:2 row_mask:0xf bank_mask:0xf
	v_fmac_f32_dpp v185, v107, v155 row_shr:2 row_mask:0xf bank_mask:0xf
	v_fmac_f32_dpp v176, v116, v140 row_shl:15 row_mask:0xf bank_mask:0xf
	v_fmac_f32_dpp v177, v117, v141 row_shl:15 row_mask:0xf bank_mask:0xf
	v_fmac_f32_dpp v178, v118, v142 row_shl:15 row_mask:0xf bank_mask:0xf
	v_fmac_f32_dpp v179, v119, v143 row_shl:15 row_mask:0xf bank_mask:0xf
	v_fmac_f32_dpp v182, v112, v144 row_shl:15 row_mask:0xf bank_mask:0xf
	v_fmac_f32_dpp v183, v113, v145 row_shl:15 row_mask:0xf bank_mask:0xf
	v_fmac_f32_dpp v184, v114, v146 row_shl:15 row_mask:0xf bank_mask:0xf
	v_fmac_f32_dpp v185, v115, v147 row_shl:15 row_mask:0xf bank_mask:0xf
	v_fmac_f32_dpp v176, v116, v148 row_shl:14 row_mask:0xf bank_mask:0xf
	v_fmac_f32_dpp v177, v117, v149 row_shl:14 row_mask:0xf bank_mask:0xf
	v_fmac_f32_dpp v178, v118, v150 row_shl:14 row_mask:0xf bank_mask:0xf
	v_fmac_f32_dpp v179, v119, v151 row_shl:14 row_mask:0xf bank_mask:0xf
	v_fmac_f32_dpp v182, v112, v152 row_shl:14 row_mask:0xf bank_mask:0xf
	v_fmac_f32_dpp v183, v113, v153 row_shl:14 row_mask:0xf bank_mask:0xf
	v_fmac_f32_dpp v184, v114, v154 row_shl:14 row_mask:0xf bank_mask:0xf
	v_fmac_f32_dpp v185, v115, v155 row_shl:14 row_mask:0xf bank_mask:0xf
	v_pk_fma_f32 v[108:109], v[132:133], v[116:117], v[156:157]
	v_pk_fma_f32 v[110:111], v[134:135], v[118:119], v[158:159]
	v_pk_fma_f32 v[104:105], v[136:137], v[112:113], v[160:161]
	v_pk_fma_f32 v[106:107], v[138:139], v[114:115], v[162:163]
	v_fmac_f32_dpp v108, v116, v140 row_shr:1 row_mask:0xf bank_mask:0xf
	v_fmac_f32_dpp v109, v117, v141 row_shr:1 row_mask:0xf bank_mask:0xf
	v_fmac_f32_dpp v110, v118, v142 row_shr:1 row_mask:0xf bank_mask:0xf
	v_fmac_f32_dpp v111, v119, v143 row_shr:1 row_mask:0xf bank_mask:0xf
	v_fmac_f32_dpp v104, v112, v144 row_shr:1 row_mask:0xf bank_mask:0xf
	v_fmac_f32_dpp v105, v113, v145 row_shr:1 row_mask:0xf bank_mask:0xf
	v_fmac_f32_dpp v106, v114, v146 row_shr:1 row_mask:0xf bank_mask:0xf
	v_fmac_f32_dpp v107, v115, v147 row_shr:1 row_mask:0xf bank_mask:0xf
	v_fmac_f32_dpp v108, v116, v148 row_shr:2 row_mask:0xf bank_mask:0xf
	v_fmac_f32_dpp v109, v117, v149 row_shr:2 row_mask:0xf bank_mask:0xf
	v_fmac_f32_dpp v110, v118, v150 row_shr:2 row_mask:0xf bank_mask:0xf
	v_fmac_f32_dpp v111, v119, v151 row_shr:2 row_mask:0xf bank_mask:0xf
	v_fmac_f32_dpp v104, v112, v152 row_shr:2 row_mask:0xf bank_mask:0xf
	v_fmac_f32_dpp v105, v113, v153 row_shr:2 row_mask:0xf bank_mask:0xf
	v_fmac_f32_dpp v106, v114, v154 row_shr:2 row_mask:0xf bank_mask:0xf
	v_fmac_f32_dpp v107, v115, v155 row_shr:2 row_mask:0xf bank_mask:0xf
	v_fmac_f32_dpp v108, v124, v140 row_shl:15 row_mask:0xf bank_mask:0xf
	v_fmac_f32_dpp v109, v125, v141 row_shl:15 row_mask:0xf bank_mask:0xf
	v_fmac_f32_dpp v110, v126, v142 row_shl:15 row_mask:0xf bank_mask:0xf
	v_fmac_f32_dpp v111, v127, v143 row_shl:15 row_mask:0xf bank_mask:0xf
	v_fmac_f32_dpp v104, v120, v144 row_shl:15 row_mask:0xf bank_mask:0xf
	v_fmac_f32_dpp v105, v121, v145 row_shl:15 row_mask:0xf bank_mask:0xf
	v_fmac_f32_dpp v106, v122, v146 row_shl:15 row_mask:0xf bank_mask:0xf
	v_fmac_f32_dpp v107, v123, v147 row_shl:15 row_mask:0xf bank_mask:0xf
	v_fmac_f32_dpp v108, v124, v148 row_shl:14 row_mask:0xf bank_mask:0xf
	v_fmac_f32_dpp v109, v125, v149 row_shl:14 row_mask:0xf bank_mask:0xf
	v_fmac_f32_dpp v110, v126, v150 row_shl:14 row_mask:0xf bank_mask:0xf
	v_fmac_f32_dpp v111, v127, v151 row_shl:14 row_mask:0xf bank_mask:0xf
	v_fmac_f32_dpp v104, v120, v152 row_shl:14 row_mask:0xf bank_mask:0xf
	v_fmac_f32_dpp v105, v121, v153 row_shl:14 row_mask:0xf bank_mask:0xf
	v_fmac_f32_dpp v106, v122, v154 row_shl:14 row_mask:0xf bank_mask:0xf
	v_fmac_f32_dpp v107, v123, v155 row_shl:14 row_mask:0xf bank_mask:0xf
	v_pk_fma_f32 v[116:117], v[132:133], v[124:125], v[156:157]
	v_pk_fma_f32 v[118:119], v[134:135], v[126:127], v[158:159]
	v_pk_fma_f32 v[112:113], v[136:137], v[120:121], v[160:161]
	v_pk_fma_f32 v[114:115], v[138:139], v[122:123], v[162:163]
	v_fmac_f32_dpp v116, v124, v140 row_shr:1 row_mask:0xf bank_mask:0xf
	v_fmac_f32_dpp v117, v125, v141 row_shr:1 row_mask:0xf bank_mask:0xf
	v_fmac_f32_dpp v118, v126, v142 row_shr:1 row_mask:0xf bank_mask:0xf
	v_fmac_f32_dpp v119, v127, v143 row_shr:1 row_mask:0xf bank_mask:0xf
	v_fmac_f32_dpp v112, v120, v144 row_shr:1 row_mask:0xf bank_mask:0xf
	v_fmac_f32_dpp v113, v121, v145 row_shr:1 row_mask:0xf bank_mask:0xf
	v_fmac_f32_dpp v114, v122, v146 row_shr:1 row_mask:0xf bank_mask:0xf
	v_fmac_f32_dpp v115, v123, v147 row_shr:1 row_mask:0xf bank_mask:0xf
	v_fmac_f32_dpp v116, v124, v148 row_shr:2 row_mask:0xf bank_mask:0xf
	v_fmac_f32_dpp v117, v125, v149 row_shr:2 row_mask:0xf bank_mask:0xf
	v_fmac_f32_dpp v118, v126, v150 row_shr:2 row_mask:0xf bank_mask:0xf
	v_fmac_f32_dpp v119, v127, v151 row_shr:2 row_mask:0xf bank_mask:0xf
	v_fmac_f32_dpp v112, v120, v152 row_shr:2 row_mask:0xf bank_mask:0xf
	v_fmac_f32_dpp v113, v121, v153 row_shr:2 row_mask:0xf bank_mask:0xf
	v_fmac_f32_dpp v114, v122, v154 row_shr:2 row_mask:0xf bank_mask:0xf
	v_fmac_f32_dpp v115, v123, v155 row_shr:2 row_mask:0xf bank_mask:0xf
	v_fmac_f32_dpp v116, v8, v140 row_shl:15 row_mask:0xf bank_mask:0xf
	v_fmac_f32_dpp v117, v9, v141 row_shl:15 row_mask:0xf bank_mask:0xf
	v_fmac_f32_dpp v118, v10, v142 row_shl:15 row_mask:0xf bank_mask:0xf
	v_fmac_f32_dpp v119, v11, v143 row_shl:15 row_mask:0xf bank_mask:0xf
	v_fmac_f32_dpp v112, v128, v144 row_shl:15 row_mask:0xf bank_mask:0xf
	v_fmac_f32_dpp v113, v129, v145 row_shl:15 row_mask:0xf bank_mask:0xf
	v_fmac_f32_dpp v114, v130, v146 row_shl:15 row_mask:0xf bank_mask:0xf
	v_fmac_f32_dpp v115, v131, v147 row_shl:15 row_mask:0xf bank_mask:0xf
	v_fmac_f32_dpp v116, v8, v148 row_shl:14 row_mask:0xf bank_mask:0xf
	v_fmac_f32_dpp v117, v9, v149 row_shl:14 row_mask:0xf bank_mask:0xf
	v_fmac_f32_dpp v118, v10, v150 row_shl:14 row_mask:0xf bank_mask:0xf
	v_fmac_f32_dpp v119, v11, v151 row_shl:14 row_mask:0xf bank_mask:0xf
	v_fmac_f32_dpp v112, v128, v152 row_shl:14 row_mask:0xf bank_mask:0xf
	v_fmac_f32_dpp v113, v129, v153 row_shl:14 row_mask:0xf bank_mask:0xf
	v_fmac_f32_dpp v114, v130, v154 row_shl:14 row_mask:0xf bank_mask:0xf
	v_fmac_f32_dpp v115, v131, v155 row_shl:14 row_mask:0xf bank_mask:0xf
	s_waitcnt lgkmcnt(0)
	v_pk_fma_f32 v[124:125], v[132:133], v[8:9], v[156:157]
	v_pk_fma_f32 v[126:127], v[134:135], v[10:11], v[158:159]
	v_pk_fma_f32 v[120:121], v[136:137], v[128:129], v[160:161]
	v_pk_fma_f32 v[122:123], v[138:139], v[130:131], v[162:163]
	v_fmac_f32_dpp v124, v8, v140 row_shr:1 row_mask:0xf bank_mask:0xf
	v_fmac_f32_dpp v125, v9, v141 row_shr:1 row_mask:0xf bank_mask:0xf
	v_fmac_f32_dpp v126, v10, v142 row_shr:1 row_mask:0xf bank_mask:0xf
	v_fmac_f32_dpp v127, v11, v143 row_shr:1 row_mask:0xf bank_mask:0xf
	v_fmac_f32_dpp v120, v128, v144 row_shr:1 row_mask:0xf bank_mask:0xf
	v_fmac_f32_dpp v121, v129, v145 row_shr:1 row_mask:0xf bank_mask:0xf
	v_fmac_f32_dpp v122, v130, v146 row_shr:1 row_mask:0xf bank_mask:0xf
	v_fmac_f32_dpp v123, v131, v147 row_shr:1 row_mask:0xf bank_mask:0xf
	v_fmac_f32_dpp v124, v8, v148 row_shr:2 row_mask:0xf bank_mask:0xf
	v_fmac_f32_dpp v125, v9, v149 row_shr:2 row_mask:0xf bank_mask:0xf
	v_fmac_f32_dpp v126, v10, v150 row_shr:2 row_mask:0xf bank_mask:0xf
	v_fmac_f32_dpp v127, v11, v151 row_shr:2 row_mask:0xf bank_mask:0xf
	v_fmac_f32_dpp v120, v128, v152 row_shr:2 row_mask:0xf bank_mask:0xf
	v_fmac_f32_dpp v121, v129, v153 row_shr:2 row_mask:0xf bank_mask:0xf
	v_fmac_f32_dpp v122, v130, v154 row_shr:2 row_mask:0xf bank_mask:0xf
	v_fmac_f32_dpp v123, v131, v155 row_shr:2 row_mask:0xf bank_mask:0xf
	v_fmac_f32_dpp v124, v246, v140 row_shl:15 row_mask:0xf bank_mask:0xf
	v_fmac_f32_dpp v125, v247, v141 row_shl:15 row_mask:0xf bank_mask:0xf
	v_fmac_f32_dpp v126, v248, v142 row_shl:15 row_mask:0xf bank_mask:0xf
	v_fmac_f32_dpp v127, v249, v143 row_shl:15 row_mask:0xf bank_mask:0xf
	v_fmac_f32_dpp v120, v250, v144 row_shl:15 row_mask:0xf bank_mask:0xf
	v_fmac_f32_dpp v121, v251, v145 row_shl:15 row_mask:0xf bank_mask:0xf
	v_fmac_f32_dpp v122, v252, v146 row_shl:15 row_mask:0xf bank_mask:0xf
	v_fmac_f32_dpp v123, v253, v147 row_shl:15 row_mask:0xf bank_mask:0xf
	v_fmac_f32_dpp v124, v246, v148 row_shl:14 row_mask:0xf bank_mask:0xf
	v_fmac_f32_dpp v125, v247, v149 row_shl:14 row_mask:0xf bank_mask:0xf
	v_fmac_f32_dpp v126, v248, v150 row_shl:14 row_mask:0xf bank_mask:0xf
	v_fmac_f32_dpp v127, v249, v151 row_shl:14 row_mask:0xf bank_mask:0xf
	v_fmac_f32_dpp v120, v250, v152 row_shl:14 row_mask:0xf bank_mask:0xf
	v_fmac_f32_dpp v121, v251, v153 row_shl:14 row_mask:0xf bank_mask:0xf
	v_fmac_f32_dpp v122, v252, v154 row_shl:14 row_mask:0xf bank_mask:0xf
	v_fmac_f32_dpp v123, v253, v155 row_shl:14 row_mask:0xf bank_mask:0xf
	s_mov_b32 exec_lo, 0xc000c000
	s_mov_b32 exec_hi, 0xc000c000
	ds_read_b128 v[246:249], v234 offset:512
	ds_read_b128 v[250:253], v234 offset:528
	s_mov_b64 exec, -1
	s_waitcnt vmcnt(4)
	v_pk_fma_f32 v[8:9], v[194:195], v[76:77], v[226:227]
	v_pk_fma_f32 v[10:11], v[196:197], v[78:79], v[228:229]
	v_pk_fma_f32 v[128:129], v[198:199], v[72:73], v[230:231]
	v_pk_fma_f32 v[130:131], v[200:201], v[74:75], v[232:233]
	v_fmac_f32_dpp v8, v76, v202 row_shr:1 row_mask:0xf bank_mask:0xf
	v_fmac_f32_dpp v9, v77, v203 row_shr:1 row_mask:0xf bank_mask:0xf
	v_fmac_f32_dpp v10, v78, v204 row_shr:1 row_mask:0xf bank_mask:0xf
	v_fmac_f32_dpp v11, v79, v205 row_shr:1 row_mask:0xf bank_mask:0xf
	v_fmac_f32_dpp v128, v72, v206 row_shr:1 row_mask:0xf bank_mask:0xf
	v_fmac_f32_dpp v129, v73, v207 row_shr:1 row_mask:0xf bank_mask:0xf
	v_fmac_f32_dpp v130, v74, v208 row_shr:1 row_mask:0xf bank_mask:0xf
	v_fmac_f32_dpp v131, v75, v209 row_shr:1 row_mask:0xf bank_mask:0xf
	v_fmac_f32_dpp v8, v76, v210 row_shr:2 row_mask:0xf bank_mask:0xf
	v_fmac_f32_dpp v9, v77, v211 row_shr:2 row_mask:0xf bank_mask:0xf
	v_fmac_f32_dpp v10, v78, v212 row_shr:2 row_mask:0xf bank_mask:0xf
	v_fmac_f32_dpp v11, v79, v213 row_shr:2 row_mask:0xf bank_mask:0xf
	v_fmac_f32_dpp v128, v72, v214 row_shr:2 row_mask:0xf bank_mask:0xf
	v_fmac_f32_dpp v129, v73, v215 row_shr:2 row_mask:0xf bank_mask:0xf
	v_fmac_f32_dpp v130, v74, v216 row_shr:2 row_mask:0xf bank_mask:0xf
	v_fmac_f32_dpp v131, v75, v217 row_shr:2 row_mask:0xf bank_mask:0xf
	v_fmac_f32_dpp v8, v84, v202 row_shl:15 row_mask:0xf bank_mask:0xf
	v_fmac_f32_dpp v9, v85, v203 row_shl:15 row_mask:0xf bank_mask:0xf
	v_fmac_f32_dpp v10, v86, v204 row_shl:15 row_mask:0xf bank_mask:0xf
	v_fmac_f32_dpp v11, v87, v205 row_shl:15 row_mask:0xf bank_mask:0xf
	v_fmac_f32_dpp v128, v80, v206 row_shl:15 row_mask:0xf bank_mask:0xf
	v_fmac_f32_dpp v129, v81, v207 row_shl:15 row_mask:0xf bank_mask:0xf
	v_fmac_f32_dpp v130, v82, v208 row_shl:15 row_mask:0xf bank_mask:0xf
	v_fmac_f32_dpp v131, v83, v209 row_shl:15 row_mask:0xf bank_mask:0xf
	v_fmac_f32_dpp v8, v84, v210 row_shl:14 row_mask:0xf bank_mask:0xf
	v_fmac_f32_dpp v9, v85, v211 row_shl:14 row_mask:0xf bank_mask:0xf
	v_fmac_f32_dpp v10, v86, v212 row_shl:14 row_mask:0xf bank_mask:0xf
	v_fmac_f32_dpp v11, v87, v213 row_shl:14 row_mask:0xf bank_mask:0xf
	v_fmac_f32_dpp v128, v80, v214 row_shl:14 row_mask:0xf bank_mask:0xf
	v_fmac_f32_dpp v129, v81, v215 row_shl:14 row_mask:0xf bank_mask:0xf
	v_fmac_f32_dpp v130, v82, v216 row_shl:14 row_mask:0xf bank_mask:0xf
	v_fmac_f32_dpp v131, v83, v217 row_shl:14 row_mask:0xf bank_mask:0xf
	v_pk_fma_f32 v[76:77], v[194:195], v[84:85], v[226:227]
	v_pk_fma_f32 v[78:79], v[196:197], v[86:87], v[228:229]
	v_pk_fma_f32 v[72:73], v[198:199], v[80:81], v[230:231]
	v_pk_fma_f32 v[74:75], v[200:201], v[82:83], v[232:233]
	v_fmac_f32_dpp v76, v84, v202 row_shr:1 row_mask:0xf bank_mask:0xf
	v_fmac_f32_dpp v77, v85, v203 row_shr:1 row_mask:0xf bank_mask:0xf
	v_fmac_f32_dpp v78, v86, v204 row_shr:1 row_mask:0xf bank_mask:0xf
	v_fmac_f32_dpp v79, v87, v205 row_shr:1 row_mask:0xf bank_mask:0xf
	v_fmac_f32_dpp v72, v80, v206 row_shr:1 row_mask:0xf bank_mask:0xf
	v_fmac_f32_dpp v73, v81, v207 row_shr:1 row_mask:0xf bank_mask:0xf
	v_fmac_f32_dpp v74, v82, v208 row_shr:1 row_mask:0xf bank_mask:0xf
	v_fmac_f32_dpp v75, v83, v209 row_shr:1 row_mask:0xf bank_mask:0xf
	v_fmac_f32_dpp v76, v84, v210 row_shr:2 row_mask:0xf bank_mask:0xf
	v_fmac_f32_dpp v77, v85, v211 row_shr:2 row_mask:0xf bank_mask:0xf
	v_fmac_f32_dpp v78, v86, v212 row_shr:2 row_mask:0xf bank_mask:0xf
	v_fmac_f32_dpp v79, v87, v213 row_shr:2 row_mask:0xf bank_mask:0xf
	v_fmac_f32_dpp v72, v80, v214 row_shr:2 row_mask:0xf bank_mask:0xf
	v_fmac_f32_dpp v73, v81, v215 row_shr:2 row_mask:0xf bank_mask:0xf
	v_fmac_f32_dpp v74, v82, v216 row_shr:2 row_mask:0xf bank_mask:0xf
	v_fmac_f32_dpp v75, v83, v217 row_shr:2 row_mask:0xf bank_mask:0xf
	v_fmac_f32_dpp v76, v92, v202 row_shl:15 row_mask:0xf bank_mask:0xf
	v_fmac_f32_dpp v77, v93, v203 row_shl:15 row_mask:0xf bank_mask:0xf
	v_fmac_f32_dpp v78, v94, v204 row_shl:15 row_mask:0xf bank_mask:0xf
	v_fmac_f32_dpp v79, v95, v205 row_shl:15 row_mask:0xf bank_mask:0xf
	v_fmac_f32_dpp v72, v88, v206 row_shl:15 row_mask:0xf bank_mask:0xf
	v_fmac_f32_dpp v73, v89, v207 row_shl:15 row_mask:0xf bank_mask:0xf
	v_fmac_f32_dpp v74, v90, v208 row_shl:15 row_mask:0xf bank_mask:0xf
	v_fmac_f32_dpp v75, v91, v209 row_shl:15 row_mask:0xf bank_mask:0xf
	v_fmac_f32_dpp v76, v92, v210 row_shl:14 row_mask:0xf bank_mask:0xf
	v_fmac_f32_dpp v77, v93, v211 row_shl:14 row_mask:0xf bank_mask:0xf
	v_fmac_f32_dpp v78, v94, v212 row_shl:14 row_mask:0xf bank_mask:0xf
	v_fmac_f32_dpp v79, v95, v213 row_shl:14 row_mask:0xf bank_mask:0xf
	v_fmac_f32_dpp v72, v88, v214 row_shl:14 row_mask:0xf bank_mask:0xf
	v_fmac_f32_dpp v73, v89, v215 row_shl:14 row_mask:0xf bank_mask:0xf
	v_fmac_f32_dpp v74, v90, v216 row_shl:14 row_mask:0xf bank_mask:0xf
	v_fmac_f32_dpp v75, v91, v217 row_shl:14 row_mask:0xf bank_mask:0xf
	v_pk_fma_f32 v[84:85], v[194:195], v[92:93], v[226:227]
	v_pk_fma_f32 v[86:87], v[196:197], v[94:95], v[228:229]
	v_pk_fma_f32 v[80:81], v[198:199], v[88:89], v[230:231]
	v_pk_fma_f32 v[82:83], v[200:201], v[90:91], v[232:233]
	v_fmac_f32_dpp v84, v92, v202 row_shr:1 row_mask:0xf bank_mask:0xf
	v_fmac_f32_dpp v85, v93, v203 row_shr:1 row_mask:0xf bank_mask:0xf
	v_fmac_f32_dpp v86, v94, v204 row_shr:1 row_mask:0xf bank_mask:0xf
	v_fmac_f32_dpp v87, v95, v205 row_shr:1 row_mask:0xf bank_mask:0xf
	v_fmac_f32_dpp v80, v88, v206 row_shr:1 row_mask:0xf bank_mask:0xf
	v_fmac_f32_dpp v81, v89, v207 row_shr:1 row_mask:0xf bank_mask:0xf
	v_fmac_f32_dpp v82, v90, v208 row_shr:1 row_mask:0xf bank_mask:0xf
	v_fmac_f32_dpp v83, v91, v209 row_shr:1 row_mask:0xf bank_mask:0xf
	v_fmac_f32_dpp v84, v92, v210 row_shr:2 row_mask:0xf bank_mask:0xf
	v_fmac_f32_dpp v85, v93, v211 row_shr:2 row_mask:0xf bank_mask:0xf
	v_fmac_f32_dpp v86, v94, v212 row_shr:2 row_mask:0xf bank_mask:0xf
	v_fmac_f32_dpp v87, v95, v213 row_shr:2 row_mask:0xf bank_mask:0xf
	v_fmac_f32_dpp v80, v88, v214 row_shr:2 row_mask:0xf bank_mask:0xf
	v_fmac_f32_dpp v81, v89, v215 row_shr:2 row_mask:0xf bank_mask:0xf
	v_fmac_f32_dpp v82, v90, v216 row_shr:2 row_mask:0xf bank_mask:0xf
	v_fmac_f32_dpp v83, v91, v217 row_shr:2 row_mask:0xf bank_mask:0xf
	v_fmac_f32_dpp v84, v100, v202 row_shl:15 row_mask:0xf bank_mask:0xf
	v_fmac_f32_dpp v85, v101, v203 row_shl:15 row_mask:0xf bank_mask:0xf
	v_fmac_f32_dpp v86, v102, v204 row_shl:15 row_mask:0xf bank_mask:0xf
	v_fmac_f32_dpp v87, v103, v205 row_shl:15 row_mask:0xf bank_mask:0xf
	v_fmac_f32_dpp v80, v96, v206 row_shl:15 row_mask:0xf bank_mask:0xf
	v_fmac_f32_dpp v81, v97, v207 row_shl:15 row_mask:0xf bank_mask:0xf
	v_fmac_f32_dpp v82, v98, v208 row_shl:15 row_mask:0xf bank_mask:0xf
	v_fmac_f32_dpp v83, v99, v209 row_shl:15 row_mask:0xf bank_mask:0xf
	v_fmac_f32_dpp v84, v100, v210 row_shl:14 row_mask:0xf bank_mask:0xf
	v_fmac_f32_dpp v85, v101, v211 row_shl:14 row_mask:0xf bank_mask:0xf
	v_fmac_f32_dpp v86, v102, v212 row_shl:14 row_mask:0xf bank_mask:0xf
	v_fmac_f32_dpp v87, v103, v213 row_shl:14 row_mask:0xf bank_mask:0xf
	v_fmac_f32_dpp v80, v96, v214 row_shl:14 row_mask:0xf bank_mask:0xf
	v_fmac_f32_dpp v81, v97, v215 row_shl:14 row_mask:0xf bank_mask:0xf
	v_fmac_f32_dpp v82, v98, v216 row_shl:14 row_mask:0xf bank_mask:0xf
	v_fmac_f32_dpp v83, v99, v217 row_shl:14 row_mask:0xf bank_mask:0xf
	s_waitcnt lgkmcnt(0)
	v_pk_fma_f32 v[92:93], v[194:195], v[100:101], v[226:227]
	v_pk_fma_f32 v[94:95], v[196:197], v[102:103], v[228:229]
	v_pk_fma_f32 v[88:89], v[198:199], v[96:97], v[230:231]
	v_pk_fma_f32 v[90:91], v[200:201], v[98:99], v[232:233]
	v_fmac_f32_dpp v92, v100, v202 row_shr:1 row_mask:0xf bank_mask:0xf
	v_fmac_f32_dpp v93, v101, v203 row_shr:1 row_mask:0xf bank_mask:0xf
	v_fmac_f32_dpp v94, v102, v204 row_shr:1 row_mask:0xf bank_mask:0xf
	v_fmac_f32_dpp v95, v103, v205 row_shr:1 row_mask:0xf bank_mask:0xf
	v_fmac_f32_dpp v88, v96, v206 row_shr:1 row_mask:0xf bank_mask:0xf
	v_fmac_f32_dpp v89, v97, v207 row_shr:1 row_mask:0xf bank_mask:0xf
	v_fmac_f32_dpp v90, v98, v208 row_shr:1 row_mask:0xf bank_mask:0xf
	v_fmac_f32_dpp v91, v99, v209 row_shr:1 row_mask:0xf bank_mask:0xf
	v_fmac_f32_dpp v92, v100, v210 row_shr:2 row_mask:0xf bank_mask:0xf
	v_fmac_f32_dpp v93, v101, v211 row_shr:2 row_mask:0xf bank_mask:0xf
	v_fmac_f32_dpp v94, v102, v212 row_shr:2 row_mask:0xf bank_mask:0xf
	v_fmac_f32_dpp v95, v103, v213 row_shr:2 row_mask:0xf bank_mask:0xf
	v_fmac_f32_dpp v88, v96, v214 row_shr:2 row_mask:0xf bank_mask:0xf
	v_fmac_f32_dpp v89, v97, v215 row_shr:2 row_mask:0xf bank_mask:0xf
	v_fmac_f32_dpp v90, v98, v216 row_shr:2 row_mask:0xf bank_mask:0xf
	v_fmac_f32_dpp v91, v99, v217 row_shr:2 row_mask:0xf bank_mask:0xf
	v_fmac_f32_dpp v92, v246, v202 row_shl:15 row_mask:0xf bank_mask:0xf
	v_fmac_f32_dpp v93, v247, v203 row_shl:15 row_mask:0xf bank_mask:0xf
	v_fmac_f32_dpp v94, v248, v204 row_shl:15 row_mask:0xf bank_mask:0xf
	v_fmac_f32_dpp v95, v249, v205 row_shl:15 row_mask:0xf bank_mask:0xf
	v_fmac_f32_dpp v88, v250, v206 row_shl:15 row_mask:0xf bank_mask:0xf
	v_fmac_f32_dpp v89, v251, v207 row_shl:15 row_mask:0xf bank_mask:0xf
	v_fmac_f32_dpp v90, v252, v208 row_shl:15 row_mask:0xf bank_mask:0xf
	v_fmac_f32_dpp v91, v253, v209 row_shl:15 row_mask:0xf bank_mask:0xf
	v_fmac_f32_dpp v92, v246, v210 row_shl:14 row_mask:0xf bank_mask:0xf
	v_fmac_f32_dpp v93, v247, v211 row_shl:14 row_mask:0xf bank_mask:0xf
	v_fmac_f32_dpp v94, v248, v212 row_shl:14 row_mask:0xf bank_mask:0xf
	v_fmac_f32_dpp v95, v249, v213 row_shl:14 row_mask:0xf bank_mask:0xf
	v_fmac_f32_dpp v88, v250, v214 row_shl:14 row_mask:0xf bank_mask:0xf
	v_fmac_f32_dpp v89, v251, v215 row_shl:14 row_mask:0xf bank_mask:0xf
	v_fmac_f32_dpp v90, v252, v216 row_shl:14 row_mask:0xf bank_mask:0xf
	v_fmac_f32_dpp v91, v253, v217 row_shl:14 row_mask:0xf bank_mask:0xf
	v_mul_f32_e32 v246, 0xbfb8aa3b, v176
	v_mul_f32_e32 v247, 0xbfb8aa3b, v177
	v_mul_f32_e32 v248, 0xbfb8aa3b, v178
	v_mul_f32_e32 v249, 0xbfb8aa3b, v179
	v_mul_f32_e32 v250, 0xbfb8aa3b, v182
	v_mul_f32_e32 v251, 0xbfb8aa3b, v183
	v_mul_f32_e32 v252, 0xbfb8aa3b, v184
	v_mul_f32_e32 v253, 0xbfb8aa3b, v185
	v_exp_f32_e32 v246, v246
	v_exp_f32_e32 v247, v247
	v_exp_f32_e32 v248, v248
	v_exp_f32_e32 v249, v249
	v_exp_f32_e32 v250, v250
	v_exp_f32_e32 v251, v251
	v_exp_f32_e32 v252, v252
	v_exp_f32_e32 v253, v253
	v_add_f32_e32 v246, 1.0, v246
	v_add_f32_e32 v247, 1.0, v247
	v_add_f32_e32 v248, 1.0, v248
	v_add_f32_e32 v249, 1.0, v249
	v_add_f32_e32 v250, 1.0, v250
	v_add_f32_e32 v251, 1.0, v251
	v_add_f32_e32 v252, 1.0, v252
	v_add_f32_e32 v253, 1.0, v253
	v_rcp_f32_e32 v246, v246
	v_rcp_f32_e32 v247, v247
	v_rcp_f32_e32 v248, v248
	v_rcp_f32_e32 v249, v249
	v_rcp_f32_e32 v250, v250
	v_rcp_f32_e32 v251, v251
	v_rcp_f32_e32 v252, v252
	v_rcp_f32_e32 v253, v253
	v_pk_mul_f32 v[176:177], v[176:177], v[246:247]
	v_pk_mul_f32 v[178:179], v[178:179], v[248:249]
	v_pk_mul_f32 v[182:183], v[182:183], v[250:251]
	v_pk_mul_f32 v[184:185], v[184:185], v[252:253]
	v_pk_mul_f32 v[176:177], v[176:177], v[8:9]
	v_pk_mul_f32 v[178:179], v[178:179], v[10:11]
	v_pk_mul_f32 v[182:183], v[182:183], v[128:129]
	v_pk_mul_f32 v[184:185], v[184:185], v[130:131]
	v_cvt_pk_bf16_f32 v176, v176, v177
	v_cvt_pk_bf16_f32 v177, v178, v179
	v_cvt_pk_bf16_f32 v178, v182, v183
	v_cvt_pk_bf16_f32 v179, v184, v185
	v_add_u32_e32 v221, 0x84000, v245
	global_store_dwordx4 v221, v[176:179], s[12:13]
	v_mul_f32_e32 v246, 0xbfb8aa3b, v108
	v_mul_f32_e32 v247, 0xbfb8aa3b, v109
	v_mul_f32_e32 v248, 0xbfb8aa3b, v110
	v_mul_f32_e32 v249, 0xbfb8aa3b, v111
	v_mul_f32_e32 v250, 0xbfb8aa3b, v104
	v_mul_f32_e32 v251, 0xbfb8aa3b, v105
	v_mul_f32_e32 v252, 0xbfb8aa3b, v106
	v_mul_f32_e32 v253, 0xbfb8aa3b, v107
	v_exp_f32_e32 v246, v246
	v_exp_f32_e32 v247, v247
	v_exp_f32_e32 v248, v248
	v_exp_f32_e32 v249, v249
	v_exp_f32_e32 v250, v250
	v_exp_f32_e32 v251, v251
	v_exp_f32_e32 v252, v252
	v_exp_f32_e32 v253, v253
	v_add_f32_e32 v246, 1.0, v246
	v_add_f32_e32 v247, 1.0, v247
	v_add_f32_e32 v248, 1.0, v248
	v_add_f32_e32 v249, 1.0, v249
	v_add_f32_e32 v250, 1.0, v250
	v_add_f32_e32 v251, 1.0, v251
	v_add_f32_e32 v252, 1.0, v252
	v_add_f32_e32 v253, 1.0, v253
	v_rcp_f32_e32 v246, v246
	v_rcp_f32_e32 v247, v247
	v_rcp_f32_e32 v248, v248
	v_rcp_f32_e32 v249, v249
	v_rcp_f32_e32 v250, v250
	v_rcp_f32_e32 v251, v251
	v_rcp_f32_e32 v252, v252
	v_rcp_f32_e32 v253, v253
	v_pk_mul_f32 v[108:109], v[108:109], v[246:247]
	v_pk_mul_f32 v[110:111], v[110:111], v[248:249]
	v_pk_mul_f32 v[104:105], v[104:105], v[250:251]
	v_pk_mul_f32 v[106:107], v[106:107], v[252:253]
	v_pk_mul_f32 v[108:109], v[108:109], v[76:77]
	v_pk_mul_f32 v[110:111], v[110:111], v[78:79]
	v_pk_mul_f32 v[104:105], v[104:105], v[72:73]
	v_pk_mul_f32 v[106:107], v[106:107], v[74:75]
	v_cvt_pk_bf16_f32 v108, v108, v109
	v_cvt_pk_bf16_f32 v109, v110, v111
	v_cvt_pk_bf16_f32 v110, v104, v105
	v_cvt_pk_bf16_f32 v111, v106, v107
	v_add_u32_e32 v240, 0x58000, v245
	global_store_dwordx4 v240, v[108:111], s[12:13]
	v_mul_f32_e32 v246, 0xbfb8aa3b, v116
	v_mul_f32_e32 v247, 0xbfb8aa3b, v117
	v_mul_f32_e32 v248, 0xbfb8aa3b, v118
	v_mul_f32_e32 v249, 0xbfb8aa3b, v119
	v_mul_f32_e32 v250, 0xbfb8aa3b, v112
	v_mul_f32_e32 v251, 0xbfb8aa3b, v113
	v_mul_f32_e32 v252, 0xbfb8aa3b, v114
	v_mul_f32_e32 v253, 0xbfb8aa3b, v115
	v_exp_f32_e32 v246, v246
	v_exp_f32_e32 v247, v247
	v_exp_f32_e32 v248, v248
	v_exp_f32_e32 v249, v249
	v_exp_f32_e32 v250, v250
	v_exp_f32_e32 v251, v251
	v_exp_f32_e32 v252, v252
	v_exp_f32_e32 v253, v253
	v_add_f32_e32 v246, 1.0, v246
	v_add_f32_e32 v247, 1.0, v247
	v_add_f32_e32 v248, 1.0, v248
	v_add_f32_e32 v249, 1.0, v249
	v_add_f32_e32 v250, 1.0, v250
	v_add_f32_e32 v251, 1.0, v251
	v_add_f32_e32 v252, 1.0, v252
	v_add_f32_e32 v253, 1.0, v253
	v_rcp_f32_e32 v246, v246
	v_rcp_f32_e32 v247, v247
	v_rcp_f32_e32 v248, v248
	v_rcp_f32_e32 v249, v249
	v_rcp_f32_e32 v250, v250
	v_rcp_f32_e32 v251, v251
	v_rcp_f32_e32 v252, v252
	v_rcp_f32_e32 v253, v253
	v_pk_mul_f32 v[116:117], v[116:117], v[246:247]
	v_pk_mul_f32 v[118:119], v[118:119], v[248:249]
	v_pk_mul_f32 v[112:113], v[112:113], v[250:251]
	v_pk_mul_f32 v[114:115], v[114:115], v[252:253]
	v_pk_mul_f32 v[116:117], v[116:117], v[84:85]
	v_pk_mul_f32 v[118:119], v[118:119], v[86:87]
	v_pk_mul_f32 v[112:113], v[112:113], v[80:81]
	v_pk_mul_f32 v[114:115], v[114:115], v[82:83]
	v_cvt_pk_bf16_f32 v116, v116, v117
	v_cvt_pk_bf16_f32 v117, v118, v119
	v_cvt_pk_bf16_f32 v118, v112, v113
	v_cvt_pk_bf16_f32 v119, v114, v115
	v_add_u32_e32 v221, 0x2c000, v245
	global_store_dwordx4 v221, v[116:119], s[12:13]
	v_mul_f32_e32 v246, 0xbfb8aa3b, v124
	v_mul_f32_e32 v247, 0xbfb8aa3b, v125
	v_mul_f32_e32 v248, 0xbfb8aa3b, v126
	v_mul_f32_e32 v249, 0xbfb8aa3b, v127
	v_mul_f32_e32 v250, 0xbfb8aa3b, v120
	v_mul_f32_e32 v251, 0xbfb8aa3b, v121
	v_mul_f32_e32 v252, 0xbfb8aa3b, v122
	v_mul_f32_e32 v253, 0xbfb8aa3b, v123
	v_exp_f32_e32 v246, v246
	v_exp_f32_e32 v247, v247
	v_exp_f32_e32 v248, v248
	v_exp_f32_e32 v249, v249
	v_exp_f32_e32 v250, v250
	v_exp_f32_e32 v251, v251
	v_exp_f32_e32 v252, v252
	v_exp_f32_e32 v253, v253
	v_add_f32_e32 v246, 1.0, v246
	v_add_f32_e32 v247, 1.0, v247
	v_add_f32_e32 v248, 1.0, v248
	v_add_f32_e32 v249, 1.0, v249
	v_add_f32_e32 v250, 1.0, v250
	v_add_f32_e32 v251, 1.0, v251
	v_add_f32_e32 v252, 1.0, v252
	v_add_f32_e32 v253, 1.0, v253
	v_rcp_f32_e32 v246, v246
	v_rcp_f32_e32 v247, v247
	v_rcp_f32_e32 v248, v248
	v_rcp_f32_e32 v249, v249
	v_rcp_f32_e32 v250, v250
	v_rcp_f32_e32 v251, v251
	v_rcp_f32_e32 v252, v252
	v_rcp_f32_e32 v253, v253
	v_pk_mul_f32 v[124:125], v[124:125], v[246:247]
	v_pk_mul_f32 v[126:127], v[126:127], v[248:249]
	v_pk_mul_f32 v[120:121], v[120:121], v[250:251]
	v_pk_mul_f32 v[122:123], v[122:123], v[252:253]
	v_pk_mul_f32 v[124:125], v[124:125], v[92:93]
	v_pk_mul_f32 v[126:127], v[126:127], v[94:95]
	v_pk_mul_f32 v[120:121], v[120:121], v[88:89]
	v_pk_mul_f32 v[122:123], v[122:123], v[90:91]
	v_cvt_pk_bf16_f32 v124, v124, v125
	v_cvt_pk_bf16_f32 v125, v126, v127
	v_cvt_pk_bf16_f32 v126, v120, v121
	v_cvt_pk_bf16_f32 v127, v122, v123
	global_store_dwordx4 v245, v[124:127], s[12:13]
	s_mov_b32 exec_lo, 0xc000c000
	s_mov_b32 exec_hi, 0xc000c000
	ds_read_b128 v[246:249], v234 offset:4096
	ds_read_b128 v[250:253], v234 offset:4112
	s_mov_b64 exec, -1
	v_pk_fma_f32 v[176:177], v[132:133], v[44:45], v[156:157]
	v_pk_fma_f32 v[178:179], v[134:135], v[46:47], v[158:159]
	v_pk_fma_f32 v[182:183], v[136:137], v[40:41], v[160:161]
	v_pk_fma_f32 v[184:185], v[138:139], v[42:43], v[162:163]
	v_fmac_f32_dpp v176, v44, v140 row_shr:1 row_mask:0xf bank_mask:0xf
	v_fmac_f32_dpp v177, v45, v141 row_shr:1 row_mask:0xf bank_mask:0xf
	v_fmac_f32_dpp v178, v46, v142 row_shr:1 row_mask:0xf bank_mask:0xf
	v_fmac_f32_dpp v179, v47, v143 row_shr:1 row_mask:0xf bank_mask:0xf
	v_fmac_f32_dpp v182, v40, v144 row_shr:1 row_mask:0xf bank_mask:0xf
	v_fmac_f32_dpp v183, v41, v145 row_shr:1 row_mask:0xf bank_mask:0xf
	v_fmac_f32_dpp v184, v42, v146 row_shr:1 row_mask:0xf bank_mask:0xf
	v_fmac_f32_dpp v185, v43, v147 row_shr:1 row_mask:0xf bank_mask:0xf
	v_fmac_f32_dpp v176, v44, v148 row_shr:2 row_mask:0xf bank_mask:0xf
	v_fmac_f32_dpp v177, v45, v149 row_shr:2 row_mask:0xf bank_mask:0xf
	v_fmac_f32_dpp v178, v46, v150 row_shr:2 row_mask:0xf bank_mask:0xf
	v_fmac_f32_dpp v179, v47, v151 row_shr:2 row_mask:0xf bank_mask:0xf
	v_fmac_f32_dpp v182, v40, v152 row_shr:2 row_mask:0xf bank_mask:0xf
	v_fmac_f32_dpp v183, v41, v153 row_shr:2 row_mask:0xf bank_mask:0xf
	v_fmac_f32_dpp v184, v42, v154 row_shr:2 row_mask:0xf bank_mask:0xf
	v_fmac_f32_dpp v185, v43, v155 row_shr:2 row_mask:0xf bank_mask:0xf
	v_fmac_f32_dpp v176, v52, v140 row_shl:15 row_mask:0xf bank_mask:0xf
	v_fmac_f32_dpp v177, v53, v141 row_shl:15 row_mask:0xf bank_mask:0xf
	v_fmac_f32_dpp v178, v54, v142 row_shl:15 row_mask:0xf bank_mask:0xf
	v_fmac_f32_dpp v179, v55, v143 row_shl:15 row_mask:0xf bank_mask:0xf
	v_fmac_f32_dpp v182, v48, v144 row_shl:15 row_mask:0xf bank_mask:0xf
	v_fmac_f32_dpp v183, v49, v145 row_shl:15 row_mask:0xf bank_mask:0xf
	v_fmac_f32_dpp v184, v50, v146 row_shl:15 row_mask:0xf bank_mask:0xf
	v_fmac_f32_dpp v185, v51, v147 row_shl:15 row_mask:0xf bank_mask:0xf
	v_fmac_f32_dpp v176, v52, v148 row_shl:14 row_mask:0xf bank_mask:0xf
	v_fmac_f32_dpp v177, v53, v149 row_shl:14 row_mask:0xf bank_mask:0xf
	v_fmac_f32_dpp v178, v54, v150 row_shl:14 row_mask:0xf bank_mask:0xf
	v_fmac_f32_dpp v179, v55, v151 row_shl:14 row_mask:0xf bank_mask:0xf
	v_fmac_f32_dpp v182, v48, v152 row_shl:14 row_mask:0xf bank_mask:0xf
	v_fmac_f32_dpp v183, v49, v153 row_shl:14 row_mask:0xf bank_mask:0xf
	v_fmac_f32_dpp v184, v50, v154 row_shl:14 row_mask:0xf bank_mask:0xf
	v_fmac_f32_dpp v185, v51, v155 row_shl:14 row_mask:0xf bank_mask:0xf
	v_pk_fma_f32 v[44:45], v[132:133], v[52:53], v[156:157]
	v_pk_fma_f32 v[46:47], v[134:135], v[54:55], v[158:159]
	v_pk_fma_f32 v[40:41], v[136:137], v[48:49], v[160:161]
	v_pk_fma_f32 v[42:43], v[138:139], v[50:51], v[162:163]
	v_fmac_f32_dpp v44, v52, v140 row_shr:1 row_mask:0xf bank_mask:0xf
	v_fmac_f32_dpp v45, v53, v141 row_shr:1 row_mask:0xf bank_mask:0xf
	v_fmac_f32_dpp v46, v54, v142 row_shr:1 row_mask:0xf bank_mask:0xf
	v_fmac_f32_dpp v47, v55, v143 row_shr:1 row_mask:0xf bank_mask:0xf
	v_fmac_f32_dpp v40, v48, v144 row_shr:1 row_mask:0xf bank_mask:0xf
	v_fmac_f32_dpp v41, v49, v145 row_shr:1 row_mask:0xf bank_mask:0xf
	v_fmac_f32_dpp v42, v50, v146 row_shr:1 row_mask:0xf bank_mask:0xf
	v_fmac_f32_dpp v43, v51, v147 row_shr:1 row_mask:0xf bank_mask:0xf
	v_fmac_f32_dpp v44, v52, v148 row_shr:2 row_mask:0xf bank_mask:0xf
	v_fmac_f32_dpp v45, v53, v149 row_shr:2 row_mask:0xf bank_mask:0xf
	v_fmac_f32_dpp v46, v54, v150 row_shr:2 row_mask:0xf bank_mask:0xf
	v_fmac_f32_dpp v47, v55, v151 row_shr:2 row_mask:0xf bank_mask:0xf
	v_fmac_f32_dpp v40, v48, v152 row_shr:2 row_mask:0xf bank_mask:0xf
	v_fmac_f32_dpp v41, v49, v153 row_shr:2 row_mask:0xf bank_mask:0xf
	v_fmac_f32_dpp v42, v50, v154 row_shr:2 row_mask:0xf bank_mask:0xf
	v_fmac_f32_dpp v43, v51, v155 row_shr:2 row_mask:0xf bank_mask:0xf
	v_fmac_f32_dpp v44, v60, v140 row_shl:15 row_mask:0xf bank_mask:0xf
	v_fmac_f32_dpp v45, v61, v141 row_shl:15 row_mask:0xf bank_mask:0xf
	v_fmac_f32_dpp v46, v62, v142 row_shl:15 row_mask:0xf bank_mask:0xf
	v_fmac_f32_dpp v47, v63, v143 row_shl:15 row_mask:0xf bank_mask:0xf
	v_fmac_f32_dpp v40, v56, v144 row_shl:15 row_mask:0xf bank_mask:0xf
	v_fmac_f32_dpp v41, v57, v145 row_shl:15 row_mask:0xf bank_mask:0xf
	v_fmac_f32_dpp v42, v58, v146 row_shl:15 row_mask:0xf bank_mask:0xf
	v_fmac_f32_dpp v43, v59, v147 row_shl:15 row_mask:0xf bank_mask:0xf
	v_fmac_f32_dpp v44, v60, v148 row_shl:14 row_mask:0xf bank_mask:0xf
	v_fmac_f32_dpp v45, v61, v149 row_shl:14 row_mask:0xf bank_mask:0xf
	v_fmac_f32_dpp v46, v62, v150 row_shl:14 row_mask:0xf bank_mask:0xf
	v_fmac_f32_dpp v47, v63, v151 row_shl:14 row_mask:0xf bank_mask:0xf
	v_fmac_f32_dpp v40, v56, v152 row_shl:14 row_mask:0xf bank_mask:0xf
	v_fmac_f32_dpp v41, v57, v153 row_shl:14 row_mask:0xf bank_mask:0xf
	v_fmac_f32_dpp v42, v58, v154 row_shl:14 row_mask:0xf bank_mask:0xf
	v_fmac_f32_dpp v43, v59, v155 row_shl:14 row_mask:0xf bank_mask:0xf
	v_pk_fma_f32 v[52:53], v[132:133], v[60:61], v[156:157]
	v_pk_fma_f32 v[54:55], v[134:135], v[62:63], v[158:159]
	v_pk_fma_f32 v[48:49], v[136:137], v[56:57], v[160:161]
	v_pk_fma_f32 v[50:51], v[138:139], v[58:59], v[162:163]
	v_fmac_f32_dpp v52, v60, v140 row_shr:1 row_mask:0xf bank_mask:0xf
	v_fmac_f32_dpp v53, v61, v141 row_shr:1 row_mask:0xf bank_mask:0xf
	v_fmac_f32_dpp v54, v62, v142 row_shr:1 row_mask:0xf bank_mask:0xf
	v_fmac_f32_dpp v55, v63, v143 row_shr:1 row_mask:0xf bank_mask:0xf
	v_fmac_f32_dpp v48, v56, v144 row_shr:1 row_mask:0xf bank_mask:0xf
	v_fmac_f32_dpp v49, v57, v145 row_shr:1 row_mask:0xf bank_mask:0xf
	v_fmac_f32_dpp v50, v58, v146 row_shr:1 row_mask:0xf bank_mask:0xf
	v_fmac_f32_dpp v51, v59, v147 row_shr:1 row_mask:0xf bank_mask:0xf
	v_fmac_f32_dpp v52, v60, v148 row_shr:2 row_mask:0xf bank_mask:0xf
	v_fmac_f32_dpp v53, v61, v149 row_shr:2 row_mask:0xf bank_mask:0xf
	v_fmac_f32_dpp v54, v62, v150 row_shr:2 row_mask:0xf bank_mask:0xf
	v_fmac_f32_dpp v55, v63, v151 row_shr:2 row_mask:0xf bank_mask:0xf
	v_fmac_f32_dpp v48, v56, v152 row_shr:2 row_mask:0xf bank_mask:0xf
	v_fmac_f32_dpp v49, v57, v153 row_shr:2 row_mask:0xf bank_mask:0xf
	v_fmac_f32_dpp v50, v58, v154 row_shr:2 row_mask:0xf bank_mask:0xf
	v_fmac_f32_dpp v51, v59, v155 row_shr:2 row_mask:0xf bank_mask:0xf
	v_fmac_f32_dpp v52, v68, v140 row_shl:15 row_mask:0xf bank_mask:0xf
	v_fmac_f32_dpp v53, v69, v141 row_shl:15 row_mask:0xf bank_mask:0xf
	v_fmac_f32_dpp v54, v70, v142 row_shl:15 row_mask:0xf bank_mask:0xf
	v_fmac_f32_dpp v55, v71, v143 row_shl:15 row_mask:0xf bank_mask:0xf
	v_fmac_f32_dpp v48, v64, v144 row_shl:15 row_mask:0xf bank_mask:0xf
	v_fmac_f32_dpp v49, v65, v145 row_shl:15 row_mask:0xf bank_mask:0xf
	v_fmac_f32_dpp v50, v66, v146 row_shl:15 row_mask:0xf bank_mask:0xf
	v_fmac_f32_dpp v51, v67, v147 row_shl:15 row_mask:0xf bank_mask:0xf
	v_fmac_f32_dpp v52, v68, v148 row_shl:14 row_mask:0xf bank_mask:0xf
	v_fmac_f32_dpp v53, v69, v149 row_shl:14 row_mask:0xf bank_mask:0xf
	v_fmac_f32_dpp v54, v70, v150 row_shl:14 row_mask:0xf bank_mask:0xf
	v_fmac_f32_dpp v55, v71, v151 row_shl:14 row_mask:0xf bank_mask:0xf
	v_fmac_f32_dpp v48, v64, v152 row_shl:14 row_mask:0xf bank_mask:0xf
	v_fmac_f32_dpp v49, v65, v153 row_shl:14 row_mask:0xf bank_mask:0xf
	v_fmac_f32_dpp v50, v66, v154 row_shl:14 row_mask:0xf bank_mask:0xf
	v_fmac_f32_dpp v51, v67, v155 row_shl:14 row_mask:0xf bank_mask:0xf
	s_waitcnt lgkmcnt(0)
	v_pk_fma_f32 v[60:61], v[132:133], v[68:69], v[156:157]
	v_pk_fma_f32 v[62:63], v[134:135], v[70:71], v[158:159]
	v_pk_fma_f32 v[56:57], v[136:137], v[64:65], v[160:161]
	v_pk_fma_f32 v[58:59], v[138:139], v[66:67], v[162:163]
	v_fmac_f32_dpp v60, v68, v140 row_shr:1 row_mask:0xf bank_mask:0xf
	v_fmac_f32_dpp v61, v69, v141 row_shr:1 row_mask:0xf bank_mask:0xf
	v_fmac_f32_dpp v62, v70, v142 row_shr:1 row_mask:0xf bank_mask:0xf
	v_fmac_f32_dpp v63, v71, v143 row_shr:1 row_mask:0xf bank_mask:0xf
	v_fmac_f32_dpp v56, v64, v144 row_shr:1 row_mask:0xf bank_mask:0xf
	v_fmac_f32_dpp v57, v65, v145 row_shr:1 row_mask:0xf bank_mask:0xf
	v_fmac_f32_dpp v58, v66, v146 row_shr:1 row_mask:0xf bank_mask:0xf
	v_fmac_f32_dpp v59, v67, v147 row_shr:1 row_mask:0xf bank_mask:0xf
	v_fmac_f32_dpp v60, v68, v148 row_shr:2 row_mask:0xf bank_mask:0xf
	v_fmac_f32_dpp v61, v69, v149 row_shr:2 row_mask:0xf bank_mask:0xf
	v_fmac_f32_dpp v62, v70, v150 row_shr:2 row_mask:0xf bank_mask:0xf
	v_fmac_f32_dpp v63, v71, v151 row_shr:2 row_mask:0xf bank_mask:0xf
	v_fmac_f32_dpp v56, v64, v152 row_shr:2 row_mask:0xf bank_mask:0xf
	v_fmac_f32_dpp v57, v65, v153 row_shr:2 row_mask:0xf bank_mask:0xf
	v_fmac_f32_dpp v58, v66, v154 row_shr:2 row_mask:0xf bank_mask:0xf
	v_fmac_f32_dpp v59, v67, v155 row_shr:2 row_mask:0xf bank_mask:0xf
	v_fmac_f32_dpp v60, v246, v140 row_shl:15 row_mask:0xf bank_mask:0xf
	v_fmac_f32_dpp v61, v247, v141 row_shl:15 row_mask:0xf bank_mask:0xf
	v_fmac_f32_dpp v62, v248, v142 row_shl:15 row_mask:0xf bank_mask:0xf
	v_fmac_f32_dpp v63, v249, v143 row_shl:15 row_mask:0xf bank_mask:0xf
	v_fmac_f32_dpp v56, v250, v144 row_shl:15 row_mask:0xf bank_mask:0xf
	v_fmac_f32_dpp v57, v251, v145 row_shl:15 row_mask:0xf bank_mask:0xf
	v_fmac_f32_dpp v58, v252, v146 row_shl:15 row_mask:0xf bank_mask:0xf
	v_fmac_f32_dpp v59, v253, v147 row_shl:15 row_mask:0xf bank_mask:0xf
	v_fmac_f32_dpp v60, v246, v148 row_shl:14 row_mask:0xf bank_mask:0xf
	v_fmac_f32_dpp v61, v247, v149 row_shl:14 row_mask:0xf bank_mask:0xf
	v_fmac_f32_dpp v62, v248, v150 row_shl:14 row_mask:0xf bank_mask:0xf
	v_fmac_f32_dpp v63, v249, v151 row_shl:14 row_mask:0xf bank_mask:0xf
	v_fmac_f32_dpp v56, v250, v152 row_shl:14 row_mask:0xf bank_mask:0xf
	v_fmac_f32_dpp v57, v251, v153 row_shl:14 row_mask:0xf bank_mask:0xf
	v_fmac_f32_dpp v58, v252, v154 row_shl:14 row_mask:0xf bank_mask:0xf
	v_fmac_f32_dpp v59, v253, v155 row_shl:14 row_mask:0xf bank_mask:0xf
	s_lshl_b32 s37, s24, 8
	v_cndmask_b32_e64 v132, 0, 1, s[10:11]
	s_or_b32 s36, s37, 16
	s_or_b32 s25, s37, 32
	s_or_b32 s23, s37, 48
	v_mov_b32_e32 v156, 0
	v_cmp_ne_u32_e64 s[12:13], 1, v132
	s_andn2_b64 vcc, exec, s[10:11]
	v_mov_b32_e32 v157, 0
	v_mov_b32_e32 v158, 0
	v_mov_b32_e32 v159, 0
	v_mov_b32_e32 v160, 0
	v_mov_b32_e32 v161, 0
	v_mov_b32_e32 v162, 0
	v_mov_b32_e32 v163, 0
	v_mov_b32_e32 v148, 0
	v_mov_b32_e32 v149, 0
	v_mov_b32_e32 v150, 0
	v_mov_b32_e32 v151, 0
	v_mov_b32_e32 v152, 0
	v_mov_b32_e32 v153, 0
	v_mov_b32_e32 v154, 0
	v_mov_b32_e32 v155, 0
	v_mov_b32_e32 v140, 0
	v_mov_b32_e32 v141, 0
	v_mov_b32_e32 v142, 0
	v_mov_b32_e32 v143, 0
	v_mov_b32_e32 v144, 0
	v_mov_b32_e32 v145, 0
	v_mov_b32_e32 v146, 0
	v_mov_b32_e32 v147, 0
	v_mov_b32_e32 v132, 0
	v_mov_b32_e32 v133, 0
	v_mov_b32_e32 v134, 0
	v_mov_b32_e32 v135, 0
	v_mov_b32_e32 v136, 0
	v_mov_b32_e32 v137, 0
	v_mov_b32_e32 v138, 0
	v_mov_b32_e32 v139, 0
	s_cbranch_vccnz .LBB0_1072
	s_cmp_eq_u32 s24, s66
	s_cbranch_scc1 .LBB0_1072
	v_add_u32_e32 v132, s37, v3
	v_ashrrev_i32_e32 v133, 31, v132
	v_lshlrev_b64 v[132:133], 7, v[132:133]
	v_lshl_add_u64 v[132:133], v[170:171], 0, v[132:133]
	global_load_dwordx4 v[156:159], v[132:133], off
	global_load_dwordx4 v[160:163], v[132:133], off offset:16
	v_add_u32_e32 v132, s36, v3
	v_ashrrev_i32_e32 v133, 31, v132
	v_lshlrev_b64 v[132:133], 7, v[132:133]
	v_lshl_add_u64 v[132:133], v[170:171], 0, v[132:133]
	global_load_dwordx4 v[148:151], v[132:133], off
	global_load_dwordx4 v[152:155], v[132:133], off offset:16
	v_add_u32_e32 v132, s25, v3
	v_ashrrev_i32_e32 v133, 31, v132
	v_lshlrev_b64 v[132:133], 7, v[132:133]
	v_lshl_add_u64 v[132:133], v[170:171], 0, v[132:133]
	global_load_dwordx4 v[140:143], v[132:133], off
	global_load_dwordx4 v[144:147], v[132:133], off offset:16
	v_add_u32_e32 v132, s23, v3
	v_ashrrev_i32_e32 v133, 31, v132
	v_lshlrev_b64 v[132:133], 7, v[132:133]
	v_lshl_add_u64 v[136:137], v[170:171], 0, v[132:133]
	global_load_dwordx4 v[132:135], v[136:137], off
	s_nop 0
	global_load_dwordx4 v[136:139], v[136:137], off offset:16
.LBB0_1072:
	s_waitcnt lgkmcnt(0)
	s_and_b64 vcc, exec, s[12:13]
	s_mov_b32 exec_lo, 0xc000c000
	s_mov_b32 exec_hi, 0xc000c000
	ds_read_b128 v[246:249], v234 offset:4608
	ds_read_b128 v[250:253], v234 offset:4624
	s_mov_b64 exec, -1
	v_pk_fma_f32 v[68:69], v[194:195], v[12:13], v[226:227]
	v_pk_fma_f32 v[70:71], v[196:197], v[14:15], v[228:229]
	v_pk_fma_f32 v[64:65], v[198:199], v[4:5], v[230:231]
	v_pk_fma_f32 v[66:67], v[200:201], v[6:7], v[232:233]
	v_fmac_f32_dpp v68, v12, v202 row_shr:1 row_mask:0xf bank_mask:0xf
	v_fmac_f32_dpp v69, v13, v203 row_shr:1 row_mask:0xf bank_mask:0xf
	v_fmac_f32_dpp v70, v14, v204 row_shr:1 row_mask:0xf bank_mask:0xf
	v_fmac_f32_dpp v71, v15, v205 row_shr:1 row_mask:0xf bank_mask:0xf
	v_fmac_f32_dpp v64, v4, v206 row_shr:1 row_mask:0xf bank_mask:0xf
	v_fmac_f32_dpp v65, v5, v207 row_shr:1 row_mask:0xf bank_mask:0xf
	v_fmac_f32_dpp v66, v6, v208 row_shr:1 row_mask:0xf bank_mask:0xf
	v_fmac_f32_dpp v67, v7, v209 row_shr:1 row_mask:0xf bank_mask:0xf
	v_fmac_f32_dpp v68, v12, v210 row_shr:2 row_mask:0xf bank_mask:0xf
	v_fmac_f32_dpp v69, v13, v211 row_shr:2 row_mask:0xf bank_mask:0xf
	v_fmac_f32_dpp v70, v14, v212 row_shr:2 row_mask:0xf bank_mask:0xf
	v_fmac_f32_dpp v71, v15, v213 row_shr:2 row_mask:0xf bank_mask:0xf
	v_fmac_f32_dpp v64, v4, v214 row_shr:2 row_mask:0xf bank_mask:0xf
	v_fmac_f32_dpp v65, v5, v215 row_shr:2 row_mask:0xf bank_mask:0xf
	v_fmac_f32_dpp v66, v6, v216 row_shr:2 row_mask:0xf bank_mask:0xf
	v_fmac_f32_dpp v67, v7, v217 row_shr:2 row_mask:0xf bank_mask:0xf
	v_fmac_f32_dpp v68, v20, v202 row_shl:15 row_mask:0xf bank_mask:0xf
	v_fmac_f32_dpp v69, v21, v203 row_shl:15 row_mask:0xf bank_mask:0xf
	v_fmac_f32_dpp v70, v22, v204 row_shl:15 row_mask:0xf bank_mask:0xf
	v_fmac_f32_dpp v71, v23, v205 row_shl:15 row_mask:0xf bank_mask:0xf
	v_fmac_f32_dpp v64, v16, v206 row_shl:15 row_mask:0xf bank_mask:0xf
	v_fmac_f32_dpp v65, v17, v207 row_shl:15 row_mask:0xf bank_mask:0xf
	v_fmac_f32_dpp v66, v18, v208 row_shl:15 row_mask:0xf bank_mask:0xf
	v_fmac_f32_dpp v67, v19, v209 row_shl:15 row_mask:0xf bank_mask:0xf
	v_fmac_f32_dpp v68, v20, v210 row_shl:14 row_mask:0xf bank_mask:0xf
	v_fmac_f32_dpp v69, v21, v211 row_shl:14 row_mask:0xf bank_mask:0xf
	v_fmac_f32_dpp v70, v22, v212 row_shl:14 row_mask:0xf bank_mask:0xf
	v_fmac_f32_dpp v71, v23, v213 row_shl:14 row_mask:0xf bank_mask:0xf
	v_fmac_f32_dpp v64, v16, v214 row_shl:14 row_mask:0xf bank_mask:0xf
	v_fmac_f32_dpp v65, v17, v215 row_shl:14 row_mask:0xf bank_mask:0xf
	v_fmac_f32_dpp v66, v18, v216 row_shl:14 row_mask:0xf bank_mask:0xf
	v_fmac_f32_dpp v67, v19, v217 row_shl:14 row_mask:0xf bank_mask:0xf
	v_pk_fma_f32 v[12:13], v[194:195], v[20:21], v[226:227]
	v_pk_fma_f32 v[14:15], v[196:197], v[22:23], v[228:229]
	v_pk_fma_f32 v[4:5], v[198:199], v[16:17], v[230:231]
	v_pk_fma_f32 v[6:7], v[200:201], v[18:19], v[232:233]
	v_fmac_f32_dpp v12, v20, v202 row_shr:1 row_mask:0xf bank_mask:0xf
	v_fmac_f32_dpp v13, v21, v203 row_shr:1 row_mask:0xf bank_mask:0xf
	v_fmac_f32_dpp v14, v22, v204 row_shr:1 row_mask:0xf bank_mask:0xf
	v_fmac_f32_dpp v15, v23, v205 row_shr:1 row_mask:0xf bank_mask:0xf
	v_fmac_f32_dpp v4, v16, v206 row_shr:1 row_mask:0xf bank_mask:0xf
	v_fmac_f32_dpp v5, v17, v207 row_shr:1 row_mask:0xf bank_mask:0xf
	v_fmac_f32_dpp v6, v18, v208 row_shr:1 row_mask:0xf bank_mask:0xf
	v_fmac_f32_dpp v7, v19, v209 row_shr:1 row_mask:0xf bank_mask:0xf
	v_fmac_f32_dpp v12, v20, v210 row_shr:2 row_mask:0xf bank_mask:0xf
	v_fmac_f32_dpp v13, v21, v211 row_shr:2 row_mask:0xf bank_mask:0xf
	v_fmac_f32_dpp v14, v22, v212 row_shr:2 row_mask:0xf bank_mask:0xf
	v_fmac_f32_dpp v15, v23, v213 row_shr:2 row_mask:0xf bank_mask:0xf
	v_fmac_f32_dpp v4, v16, v214 row_shr:2 row_mask:0xf bank_mask:0xf
	v_fmac_f32_dpp v5, v17, v215 row_shr:2 row_mask:0xf bank_mask:0xf
	v_fmac_f32_dpp v6, v18, v216 row_shr:2 row_mask:0xf bank_mask:0xf
	v_fmac_f32_dpp v7, v19, v217 row_shr:2 row_mask:0xf bank_mask:0xf
	v_fmac_f32_dpp v12, v28, v202 row_shl:15 row_mask:0xf bank_mask:0xf
	v_fmac_f32_dpp v13, v29, v203 row_shl:15 row_mask:0xf bank_mask:0xf
	v_fmac_f32_dpp v14, v30, v204 row_shl:15 row_mask:0xf bank_mask:0xf
	v_fmac_f32_dpp v15, v31, v205 row_shl:15 row_mask:0xf bank_mask:0xf
	v_fmac_f32_dpp v4, v24, v206 row_shl:15 row_mask:0xf bank_mask:0xf
	v_fmac_f32_dpp v5, v25, v207 row_shl:15 row_mask:0xf bank_mask:0xf
	v_fmac_f32_dpp v6, v26, v208 row_shl:15 row_mask:0xf bank_mask:0xf
	v_fmac_f32_dpp v7, v27, v209 row_shl:15 row_mask:0xf bank_mask:0xf
	v_fmac_f32_dpp v12, v28, v210 row_shl:14 row_mask:0xf bank_mask:0xf
	v_fmac_f32_dpp v13, v29, v211 row_shl:14 row_mask:0xf bank_mask:0xf
	v_fmac_f32_dpp v14, v30, v212 row_shl:14 row_mask:0xf bank_mask:0xf
	v_fmac_f32_dpp v15, v31, v213 row_shl:14 row_mask:0xf bank_mask:0xf
	v_fmac_f32_dpp v4, v24, v214 row_shl:14 row_mask:0xf bank_mask:0xf
	v_fmac_f32_dpp v5, v25, v215 row_shl:14 row_mask:0xf bank_mask:0xf
	v_fmac_f32_dpp v6, v26, v216 row_shl:14 row_mask:0xf bank_mask:0xf
	v_fmac_f32_dpp v7, v27, v217 row_shl:14 row_mask:0xf bank_mask:0xf
	v_pk_fma_f32 v[20:21], v[194:195], v[28:29], v[226:227]
	v_pk_fma_f32 v[22:23], v[196:197], v[30:31], v[228:229]
	v_pk_fma_f32 v[16:17], v[198:199], v[24:25], v[230:231]
	v_pk_fma_f32 v[18:19], v[200:201], v[26:27], v[232:233]
	v_fmac_f32_dpp v20, v28, v202 row_shr:1 row_mask:0xf bank_mask:0xf
	v_fmac_f32_dpp v21, v29, v203 row_shr:1 row_mask:0xf bank_mask:0xf
	v_fmac_f32_dpp v22, v30, v204 row_shr:1 row_mask:0xf bank_mask:0xf
	v_fmac_f32_dpp v23, v31, v205 row_shr:1 row_mask:0xf bank_mask:0xf
	v_fmac_f32_dpp v16, v24, v206 row_shr:1 row_mask:0xf bank_mask:0xf
	v_fmac_f32_dpp v17, v25, v207 row_shr:1 row_mask:0xf bank_mask:0xf
	v_fmac_f32_dpp v18, v26, v208 row_shr:1 row_mask:0xf bank_mask:0xf
	v_fmac_f32_dpp v19, v27, v209 row_shr:1 row_mask:0xf bank_mask:0xf
	v_fmac_f32_dpp v20, v28, v210 row_shr:2 row_mask:0xf bank_mask:0xf
	v_fmac_f32_dpp v21, v29, v211 row_shr:2 row_mask:0xf bank_mask:0xf
	v_fmac_f32_dpp v22, v30, v212 row_shr:2 row_mask:0xf bank_mask:0xf
	v_fmac_f32_dpp v23, v31, v213 row_shr:2 row_mask:0xf bank_mask:0xf
	v_fmac_f32_dpp v16, v24, v214 row_shr:2 row_mask:0xf bank_mask:0xf
	v_fmac_f32_dpp v17, v25, v215 row_shr:2 row_mask:0xf bank_mask:0xf
	v_fmac_f32_dpp v18, v26, v216 row_shr:2 row_mask:0xf bank_mask:0xf
	v_fmac_f32_dpp v19, v27, v217 row_shr:2 row_mask:0xf bank_mask:0xf
	v_fmac_f32_dpp v20, v36, v202 row_shl:15 row_mask:0xf bank_mask:0xf
	v_fmac_f32_dpp v21, v37, v203 row_shl:15 row_mask:0xf bank_mask:0xf
	v_fmac_f32_dpp v22, v38, v204 row_shl:15 row_mask:0xf bank_mask:0xf
	v_fmac_f32_dpp v23, v39, v205 row_shl:15 row_mask:0xf bank_mask:0xf
	v_fmac_f32_dpp v16, v32, v206 row_shl:15 row_mask:0xf bank_mask:0xf
	v_fmac_f32_dpp v17, v33, v207 row_shl:15 row_mask:0xf bank_mask:0xf
	v_fmac_f32_dpp v18, v34, v208 row_shl:15 row_mask:0xf bank_mask:0xf
	v_fmac_f32_dpp v19, v35, v209 row_shl:15 row_mask:0xf bank_mask:0xf
	v_fmac_f32_dpp v20, v36, v210 row_shl:14 row_mask:0xf bank_mask:0xf
	v_fmac_f32_dpp v21, v37, v211 row_shl:14 row_mask:0xf bank_mask:0xf
	v_fmac_f32_dpp v22, v38, v212 row_shl:14 row_mask:0xf bank_mask:0xf
	v_fmac_f32_dpp v23, v39, v213 row_shl:14 row_mask:0xf bank_mask:0xf
	v_fmac_f32_dpp v16, v32, v214 row_shl:14 row_mask:0xf bank_mask:0xf
	v_fmac_f32_dpp v17, v33, v215 row_shl:14 row_mask:0xf bank_mask:0xf
	v_fmac_f32_dpp v18, v34, v216 row_shl:14 row_mask:0xf bank_mask:0xf
	v_fmac_f32_dpp v19, v35, v217 row_shl:14 row_mask:0xf bank_mask:0xf
	s_waitcnt lgkmcnt(0)
	v_pk_fma_f32 v[28:29], v[194:195], v[36:37], v[226:227]
	v_pk_fma_f32 v[30:31], v[196:197], v[38:39], v[228:229]
	v_pk_fma_f32 v[24:25], v[198:199], v[32:33], v[230:231]
	v_pk_fma_f32 v[26:27], v[200:201], v[34:35], v[232:233]
	v_fmac_f32_dpp v28, v36, v202 row_shr:1 row_mask:0xf bank_mask:0xf
	v_fmac_f32_dpp v29, v37, v203 row_shr:1 row_mask:0xf bank_mask:0xf
	v_fmac_f32_dpp v30, v38, v204 row_shr:1 row_mask:0xf bank_mask:0xf
	v_fmac_f32_dpp v31, v39, v205 row_shr:1 row_mask:0xf bank_mask:0xf
	v_fmac_f32_dpp v24, v32, v206 row_shr:1 row_mask:0xf bank_mask:0xf
	v_fmac_f32_dpp v25, v33, v207 row_shr:1 row_mask:0xf bank_mask:0xf
	v_fmac_f32_dpp v26, v34, v208 row_shr:1 row_mask:0xf bank_mask:0xf
	v_fmac_f32_dpp v27, v35, v209 row_shr:1 row_mask:0xf bank_mask:0xf
	v_fmac_f32_dpp v28, v36, v210 row_shr:2 row_mask:0xf bank_mask:0xf
	v_fmac_f32_dpp v29, v37, v211 row_shr:2 row_mask:0xf bank_mask:0xf
	v_fmac_f32_dpp v30, v38, v212 row_shr:2 row_mask:0xf bank_mask:0xf
	v_fmac_f32_dpp v31, v39, v213 row_shr:2 row_mask:0xf bank_mask:0xf
	v_fmac_f32_dpp v24, v32, v214 row_shr:2 row_mask:0xf bank_mask:0xf
	v_fmac_f32_dpp v25, v33, v215 row_shr:2 row_mask:0xf bank_mask:0xf
	v_fmac_f32_dpp v26, v34, v216 row_shr:2 row_mask:0xf bank_mask:0xf
	v_fmac_f32_dpp v27, v35, v217 row_shr:2 row_mask:0xf bank_mask:0xf
	v_fmac_f32_dpp v28, v246, v202 row_shl:15 row_mask:0xf bank_mask:0xf
	v_fmac_f32_dpp v29, v247, v203 row_shl:15 row_mask:0xf bank_mask:0xf
	v_fmac_f32_dpp v30, v248, v204 row_shl:15 row_mask:0xf bank_mask:0xf
	v_fmac_f32_dpp v31, v249, v205 row_shl:15 row_mask:0xf bank_mask:0xf
	v_fmac_f32_dpp v24, v250, v206 row_shl:15 row_mask:0xf bank_mask:0xf
	v_fmac_f32_dpp v25, v251, v207 row_shl:15 row_mask:0xf bank_mask:0xf
	v_fmac_f32_dpp v26, v252, v208 row_shl:15 row_mask:0xf bank_mask:0xf
	v_fmac_f32_dpp v27, v253, v209 row_shl:15 row_mask:0xf bank_mask:0xf
	v_fmac_f32_dpp v28, v246, v210 row_shl:14 row_mask:0xf bank_mask:0xf
	v_fmac_f32_dpp v29, v247, v211 row_shl:14 row_mask:0xf bank_mask:0xf
	v_fmac_f32_dpp v30, v248, v212 row_shl:14 row_mask:0xf bank_mask:0xf
	v_fmac_f32_dpp v31, v249, v213 row_shl:14 row_mask:0xf bank_mask:0xf
	v_fmac_f32_dpp v24, v250, v214 row_shl:14 row_mask:0xf bank_mask:0xf
	v_fmac_f32_dpp v25, v251, v215 row_shl:14 row_mask:0xf bank_mask:0xf
	v_fmac_f32_dpp v26, v252, v216 row_shl:14 row_mask:0xf bank_mask:0xf
	v_fmac_f32_dpp v27, v253, v217 row_shl:14 row_mask:0xf bank_mask:0xf
	s_cbranch_vccnz .LBB0_1082
	s_cmp_eq_u32 s24, s66
	s_cbranch_scc1 .LBB0_1082
	s_waitcnt vmcnt(0)
	v_add_f32_e32 v156, v156, v157
	v_add_f32_e32 v157, v158, v159
	v_add_f32_e32 v156, v156, v157
	v_add_f32_e32 v157, v160, v161
	v_add_f32_e32 v158, v162, v163
	v_add_f32_e32 v157, v157, v158
	v_add_f32_e32 v156, v156, v157
	ds_bpermute_b32 v157, v186, v156
	s_waitcnt lgkmcnt(0)
	v_add_f32_e32 v156, v156, v157
	ds_bpermute_b32 v157, v187, v156
	s_and_saveexec_b64 s[34:35], s[6:7]
	s_cbranch_execz .LBB0_1075
	s_waitcnt lgkmcnt(0)
	v_add_f32_e32 v156, v156, v157
	v_fmamk_f32 v156, v156, 0x3a000000, v218
	v_mul_f32_e32 v157, 0x4f800000, v156
	v_cmp_gt_f32_e32 vcc, s49, v156
	s_nop 1
	v_cndmask_b32_e32 v156, v156, v157, vcc
	v_sqrt_f32_e32 v157, v156
	s_nop 0
	v_add_u32_e32 v158, -1, v157
	v_fma_f32 v160, -v158, v157, v156
	v_add_u32_e32 v159, 1, v157
	v_cmp_ge_f32_e64 s[10:11], 0, v160
	s_nop 1
	v_cndmask_b32_e64 v158, v157, v158, s[10:11]
	v_fma_f32 v157, -v159, v157, v156
	v_cmp_lt_f32_e64 s[10:11], 0, v157
	s_nop 1
	v_cndmask_b32_e64 v157, v158, v159, s[10:11]
	v_mul_f32_e32 v158, 0x37800000, v157
	v_cndmask_b32_e32 v157, v157, v158, vcc
	v_cmp_class_f32_e32 vcc, v156, v220
	s_nop 1
	v_cndmask_b32_e32 v156, v157, v156, vcc
	v_div_scale_f32 v157, s[10:11], v156, v156, 1.0
	v_rcp_f32_e32 v158, v157
	s_nop 0
	v_fma_f32 v159, -v157, v158, 1.0
	v_fmac_f32_e32 v158, v159, v158
	v_div_scale_f32 v159, vcc, 1.0, v156, 1.0
	v_mul_f32_e32 v160, v159, v158
	v_fma_f32 v161, -v157, v160, v159
	v_fmac_f32_e32 v160, v161, v158
	v_fma_f32 v157, -v157, v160, v159
	v_div_fmas_f32 v157, v157, v158, v160
	v_div_fixup_f32 v156, v157, v156, 1.0
	ds_write_b32 v193, v156

.LBB0_1082:
	s_add_u32 s10, s42, 0xffffff00
	s_addc_u32 s11, s75, -1
	s_and_b64 vcc, exec, s[12:13]
	s_add_u32 s34, s18, 0x16000000
	s_addc_u32 s35, s19, 0
	v_mul_f32_e32 v246, 0xbfb8aa3b, v176
	v_mul_f32_e32 v247, 0xbfb8aa3b, v177
	v_mul_f32_e32 v248, 0xbfb8aa3b, v178
	v_mul_f32_e32 v249, 0xbfb8aa3b, v179
	v_mul_f32_e32 v250, 0xbfb8aa3b, v182
	v_mul_f32_e32 v251, 0xbfb8aa3b, v183
	v_mul_f32_e32 v252, 0xbfb8aa3b, v184
	v_mul_f32_e32 v253, 0xbfb8aa3b, v185
	v_exp_f32_e32 v246, v246
	v_exp_f32_e32 v247, v247
	v_exp_f32_e32 v248, v248
	v_exp_f32_e32 v249, v249
	v_exp_f32_e32 v250, v250
	v_exp_f32_e32 v251, v251
	v_exp_f32_e32 v252, v252
	v_exp_f32_e32 v253, v253
	v_add_f32_e32 v246, 1.0, v246
	v_add_f32_e32 v247, 1.0, v247
	v_add_f32_e32 v248, 1.0, v248
	v_add_f32_e32 v249, 1.0, v249
	v_add_f32_e32 v250, 1.0, v250
	v_add_f32_e32 v251, 1.0, v251
	v_add_f32_e32 v252, 1.0, v252
	v_add_f32_e32 v253, 1.0, v253
	v_rcp_f32_e32 v246, v246
	v_rcp_f32_e32 v247, v247
	v_rcp_f32_e32 v248, v248
	v_rcp_f32_e32 v249, v249
	v_rcp_f32_e32 v250, v250
	v_rcp_f32_e32 v251, v251
	v_rcp_f32_e32 v252, v252
	v_rcp_f32_e32 v253, v253
	v_pk_mul_f32 v[176:177], v[176:177], v[246:247]
	v_pk_mul_f32 v[178:179], v[178:179], v[248:249]
	v_pk_mul_f32 v[182:183], v[182:183], v[250:251]
	v_pk_mul_f32 v[184:185], v[184:185], v[252:253]
	v_pk_mul_f32 v[176:177], v[176:177], v[68:69]
	v_pk_mul_f32 v[178:179], v[178:179], v[70:71]
	v_pk_mul_f32 v[182:183], v[182:183], v[64:65]
	v_pk_mul_f32 v[184:185], v[184:185], v[66:67]
	v_cvt_pk_bf16_f32 v176, v176, v177
	v_cvt_pk_bf16_f32 v177, v178, v179
	v_cvt_pk_bf16_f32 v178, v182, v183
	v_cvt_pk_bf16_f32 v179, v184, v185
	v_add_u32_e32 v221, 0x1e4000, v245
	global_store_dwordx4 v221, v[176:179], s[34:35]
	v_mul_f32_e32 v246, 0xbfb8aa3b, v44
	v_mul_f32_e32 v247, 0xbfb8aa3b, v45
	v_mul_f32_e32 v248, 0xbfb8aa3b, v46
	v_mul_f32_e32 v249, 0xbfb8aa3b, v47
	v_mul_f32_e32 v250, 0xbfb8aa3b, v40
	v_mul_f32_e32 v251, 0xbfb8aa3b, v41
	v_mul_f32_e32 v252, 0xbfb8aa3b, v42
	v_mul_f32_e32 v253, 0xbfb8aa3b, v43
	v_exp_f32_e32 v246, v246
	v_exp_f32_e32 v247, v247
	v_exp_f32_e32 v248, v248
	v_exp_f32_e32 v249, v249
	v_exp_f32_e32 v250, v250
	v_exp_f32_e32 v251, v251
	v_exp_f32_e32 v252, v252
	v_exp_f32_e32 v253, v253
	v_add_f32_e32 v246, 1.0, v246
	v_add_f32_e32 v247, 1.0, v247
	v_add_f32_e32 v248, 1.0, v248
	v_add_f32_e32 v249, 1.0, v249
	v_add_f32_e32 v250, 1.0, v250
	v_add_f32_e32 v251, 1.0, v251
	v_add_f32_e32 v252, 1.0, v252
	v_add_f32_e32 v253, 1.0, v253
	v_rcp_f32_e32 v246, v246
	v_rcp_f32_e32 v247, v247
	v_rcp_f32_e32 v248, v248
	v_rcp_f32_e32 v249, v249
	v_rcp_f32_e32 v250, v250
	v_rcp_f32_e32 v251, v251
	v_rcp_f32_e32 v252, v252
	v_rcp_f32_e32 v253, v253
	v_pk_mul_f32 v[44:45], v[44:45], v[246:247]
	v_pk_mul_f32 v[46:47], v[46:47], v[248:249]
	v_pk_mul_f32 v[40:41], v[40:41], v[250:251]
	v_pk_mul_f32 v[42:43], v[42:43], v[252:253]
	v_pk_mul_f32 v[44:45], v[44:45], v[12:13]
	v_pk_mul_f32 v[46:47], v[46:47], v[14:15]
	v_pk_mul_f32 v[40:41], v[40:41], v[4:5]
	v_pk_mul_f32 v[42:43], v[42:43], v[6:7]
	v_cvt_pk_bf16_f32 v44, v44, v45
	v_cvt_pk_bf16_f32 v45, v46, v47
	v_cvt_pk_bf16_f32 v46, v40, v41
	v_cvt_pk_bf16_f32 v47, v42, v43
	v_add_u32_e32 v240, 0x1b8000, v245
	global_store_dwordx4 v240, v[44:47], s[34:35]
	v_mul_f32_e32 v246, 0xbfb8aa3b, v52
	v_mul_f32_e32 v247, 0xbfb8aa3b, v53
	v_mul_f32_e32 v248, 0xbfb8aa3b, v54
	v_mul_f32_e32 v249, 0xbfb8aa3b, v55
	v_mul_f32_e32 v250, 0xbfb8aa3b, v48
	v_mul_f32_e32 v251, 0xbfb8aa3b, v49
	v_mul_f32_e32 v252, 0xbfb8aa3b, v50
	v_mul_f32_e32 v253, 0xbfb8aa3b, v51
	v_exp_f32_e32 v246, v246
	v_exp_f32_e32 v247, v247
	v_exp_f32_e32 v248, v248
	v_exp_f32_e32 v249, v249
	v_exp_f32_e32 v250, v250
	v_exp_f32_e32 v251, v251
	v_exp_f32_e32 v252, v252
	v_exp_f32_e32 v253, v253
	v_add_f32_e32 v246, 1.0, v246
	v_add_f32_e32 v247, 1.0, v247
	v_add_f32_e32 v248, 1.0, v248
	v_add_f32_e32 v249, 1.0, v249
	v_add_f32_e32 v250, 1.0, v250
	v_add_f32_e32 v251, 1.0, v251
	v_add_f32_e32 v252, 1.0, v252
	v_add_f32_e32 v253, 1.0, v253
	v_rcp_f32_e32 v246, v246
	v_rcp_f32_e32 v247, v247
	v_rcp_f32_e32 v248, v248
	v_rcp_f32_e32 v249, v249
	v_rcp_f32_e32 v250, v250
	v_rcp_f32_e32 v251, v251
	v_rcp_f32_e32 v252, v252
	v_rcp_f32_e32 v253, v253
	v_pk_mul_f32 v[52:53], v[52:53], v[246:247]
	v_pk_mul_f32 v[54:55], v[54:55], v[248:249]
	v_pk_mul_f32 v[48:49], v[48:49], v[250:251]
	v_pk_mul_f32 v[50:51], v[50:51], v[252:253]
	v_pk_mul_f32 v[52:53], v[52:53], v[20:21]
	v_pk_mul_f32 v[54:55], v[54:55], v[22:23]
	v_pk_mul_f32 v[48:49], v[48:49], v[16:17]
	v_pk_mul_f32 v[50:51], v[50:51], v[18:19]
	v_cvt_pk_bf16_f32 v52, v52, v53
	v_cvt_pk_bf16_f32 v53, v54, v55
	v_cvt_pk_bf16_f32 v54, v48, v49
	v_cvt_pk_bf16_f32 v55, v50, v51
	v_add_u32_e32 v221, 0x18c000, v245
	global_store_dwordx4 v221, v[52:55], s[34:35]
	v_mul_f32_e32 v246, 0xbfb8aa3b, v60
	v_mul_f32_e32 v247, 0xbfb8aa3b, v61
	v_mul_f32_e32 v248, 0xbfb8aa3b, v62
	v_mul_f32_e32 v249, 0xbfb8aa3b, v63
	v_mul_f32_e32 v250, 0xbfb8aa3b, v56
	v_mul_f32_e32 v251, 0xbfb8aa3b, v57
	v_mul_f32_e32 v252, 0xbfb8aa3b, v58
	v_mul_f32_e32 v253, 0xbfb8aa3b, v59
	v_exp_f32_e32 v246, v246
	v_exp_f32_e32 v247, v247
	v_exp_f32_e32 v248, v248
	v_exp_f32_e32 v249, v249
	v_exp_f32_e32 v250, v250
	v_exp_f32_e32 v251, v251
	v_exp_f32_e32 v252, v252
	v_exp_f32_e32 v253, v253
	v_add_f32_e32 v246, 1.0, v246
	v_add_f32_e32 v247, 1.0, v247
	v_add_f32_e32 v248, 1.0, v248
	v_add_f32_e32 v249, 1.0, v249
	v_add_f32_e32 v250, 1.0, v250
	v_add_f32_e32 v251, 1.0, v251
	v_add_f32_e32 v252, 1.0, v252
	v_add_f32_e32 v253, 1.0, v253
	v_rcp_f32_e32 v246, v246
	v_rcp_f32_e32 v247, v247
	v_rcp_f32_e32 v248, v248
	v_rcp_f32_e32 v249, v249
	v_rcp_f32_e32 v250, v250
	v_rcp_f32_e32 v251, v251
	v_rcp_f32_e32 v252, v252
	v_rcp_f32_e32 v253, v253
	v_pk_mul_f32 v[60:61], v[60:61], v[246:247]
	v_pk_mul_f32 v[62:63], v[62:63], v[248:249]
	v_pk_mul_f32 v[56:57], v[56:57], v[250:251]
	v_pk_mul_f32 v[58:59], v[58:59], v[252:253]
	v_pk_mul_f32 v[60:61], v[60:61], v[28:29]
	v_pk_mul_f32 v[62:63], v[62:63], v[30:31]
	v_pk_mul_f32 v[56:57], v[56:57], v[24:25]
	v_pk_mul_f32 v[58:59], v[58:59], v[26:27]
	v_cvt_pk_bf16_f32 v60, v60, v61
	v_cvt_pk_bf16_f32 v61, v62, v63
	v_cvt_pk_bf16_f32 v62, v56, v57
	v_cvt_pk_bf16_f32 v63, v58, v59
	v_add_u32_e32 v240, 0x160000, v245
	global_store_dwordx4 v240, v[60:63], s[34:35]
	s_cbranch_vccnz .LBB0_1093
	s_cmp_eq_u32 s24, s66
	s_cbranch_scc1 .LBB0_1091
	s_waitcnt vmcnt(0)
	v_add_f32_e32 v4, v156, v157
	v_add_f32_e32 v5, v158, v159
	v_add_f32_e32 v4, v4, v5
	v_add_f32_e32 v5, v160, v161
	v_add_f32_e32 v6, v162, v163
	v_add_f32_e32 v5, v5, v6
	v_add_f32_e32 v4, v4, v5
	ds_bpermute_b32 v5, v186, v4
	s_waitcnt lgkmcnt(0)
	v_add_f32_e32 v4, v4, v5
	ds_bpermute_b32 v5, v187, v4
	s_and_saveexec_b64 s[12:13], s[6:7]
	s_cbranch_execz .LBB0_1085
	s_waitcnt lgkmcnt(0)
	v_add_f32_e32 v4, v4, v5
	v_fmamk_f32 v4, v4, 0x3a000000, v218
	v_mul_f32_e32 v5, 0x4f800000, v4
	v_cmp_gt_f32_e32 vcc, s49, v4
	s_nop 1
	v_cndmask_b32_e32 v4, v4, v5, vcc
	v_sqrt_f32_e32 v5, v4
	s_nop 0
	v_add_u32_e32 v6, -1, v5
	v_fma_f32 v8, -v6, v5, v4
	v_add_u32_e32 v7, 1, v5
	v_cmp_ge_f32_e64 s[10:11], 0, v8
	s_nop 1
	v_cndmask_b32_e64 v6, v5, v6, s[10:11]
	v_fma_f32 v5, -v7, v5, v4
	v_cmp_lt_f32_e64 s[10:11], 0, v5
	s_nop 1
	v_cndmask_b32_e64 v5, v6, v7, s[10:11]
	v_mul_f32_e32 v6, 0x37800000, v5
	v_cndmask_b32_e32 v5, v5, v6, vcc
	v_cmp_class_f32_e32 vcc, v4, v220
	s_nop 1
	v_cndmask_b32_e32 v4, v5, v4, vcc
	v_div_scale_f32 v5, s[10:11], v4, v4, 1.0
	v_rcp_f32_e32 v6, v5
	s_nop 0
	v_fma_f32 v7, -v5, v6, 1.0
	v_fmac_f32_e32 v6, v7, v6
	v_div_scale_f32 v7, vcc, 1.0, v4, 1.0
	v_mul_f32_e32 v8, v7, v6
	v_fma_f32 v9, -v5, v8, v7
	v_fmac_f32_e32 v8, v9, v6
	v_fma_f32 v5, -v5, v8, v7
	v_div_fmas_f32 v5, v5, v6, v8
	v_div_fixup_f32 v4, v5, v4, 1.0
	ds_write_b32 v193, v4 offset:256
